# speedup vs baseline: 1.0049x; 1.0049x over previous
; #define LDA(dst, b, h) for (int m = 0; m < 4; ++m) for (int k = 0; k < 2; ++k) \
;     dst[m][k] = *reinterpret_cast<const bf16x8*>((char*)SA(b, h) + lds_byte(wr * 64 + m * 16 + fr, k * 32 + fq * 8))
; #define LDB(dst, b, h) for (int n = 0; n < 2; ++n) for (int k = 0; k < 2; ++k) \
;     dst[n][k] = *reinterpret_cast<const bf16x8*>((char*)SB(b, h) + lds_byte(wc * 32 + n * 16 + fr, k * 32 + fq * 8))
; #define MMA(ai, bj, At, Bt_) do { __builtin_amdgcn_s_setprio(1); \
;     for (int m = 0; m < 4; ++m) for (int n = 0; n < 2; ++n) for (int k = 0; k < 2; ++k) \
;       acc[ai][bj][m][n] = __builtin_amdgcn_mfma_f32_16x16x32_bf16(At[m][k], Bt_[n][k], acc[ai][bj][m][n], 0, 0, 0); \
;     __builtin_amdgcn_s_setprio(0); } while (0)
; #define WAIT_L(n) asm volatile("s_waitcnt lgkmcnt(" #n ")" ::: "memory")
; #define BAR __builtin_amdgcn_s_barrier()
; #define SCHED __builtin_amdgcn_sched_barrier(0)
;     ...
;       LDB(B0, 0, 0); SCHED; LDA(At, 0, 0); STAGE(SA(1, 1), A, brow + HALF, t + 1);
;       WAIT_L(8); BAR; WAIT_L(0); MMA(0, 0, At, B0); BAR; SCHED;
;       LDB(B1, 0, 1); STAGE(SB(0, 0), Bt, bcol, t + 2);
;       BAR; WAIT_L(0); MMA(0, 1, At, B1); BAR;
;       LDA(At, 0, 1); STAGE(SA(0, 0), A, brow, t + 2);
;       BAR; WAIT_L(0); MMA(1, 0, At, B0); BAR; SCHED;
.LBB0_98:
	v_add_u32_e32 v143, s2, v142
	ds_read_b128 v[146:149], v143
	ds_read_b128 v[150:153], v143 offset:1024
	ds_read_b128 v[154:157], v143 offset:2048
	ds_read_b128 v[158:161], v143 offset:3072
	s_add_u32 s66, s55, s4
	s_addc_u32 s67, s57, s5
	s_add_i32 s63, s15, 0xc000
	ds_read_b128 v[162:165], v133
	ds_read_b128 v[184:187], v133 offset:1024
	ds_read_b128 v[188:191], v134
	ds_read_b128 v[192:195], v134 offset:1024
	ds_read_b128 v[196:199], v137
	ds_read_b128 v[200:203], v137 offset:1024
	ds_read_b128 v[204:207], v139
	ds_read_b128 v[208:211], v139 offset:1024
	s_mov_b32 m0, s63
	v_lshl_add_u64 v[144:145], s[66:67], 0, v[0:1]
	s_add_i32 s59, s15, 0xe000
	global_load_lds_dwordx4 v[144:145], off
	v_lshl_add_u64 v[144:145], s[66:67], 0, v[140:141]
	s_mov_b32 m0, s59
	s_nop 0
	global_load_lds_dwordx4 v[144:145], off
	s_waitcnt lgkmcnt(8)
	s_barrier
	s_waitcnt lgkmcnt(0)
	s_waitcnt lgkmcnt(0)
	v_mfma_f32_16x16x32_bf16 v[126:129], v[162:165], v[146:149], v[126:129]
	v_mfma_f32_16x16x32_bf16 v[122:125], v[162:165], v[154:157], v[122:125]
	v_mfma_f32_16x16x32_bf16 v[118:121], v[188:191], v[146:149], v[118:121]
	v_mfma_f32_16x16x32_bf16 v[114:117], v[188:191], v[154:157], v[114:117]
	v_mfma_f32_16x16x32_bf16 v[110:113], v[196:199], v[146:149], v[110:113]
	v_mfma_f32_16x16x32_bf16 v[106:109], v[196:199], v[154:157], v[106:109]
	v_mfma_f32_16x16x32_bf16 v[102:105], v[204:207], v[146:149], v[102:105]
	v_mfma_f32_16x16x32_bf16 v[98:101], v[204:207], v[154:157], v[98:101]
	v_mfma_f32_16x16x32_bf16 v[126:129], v[184:187], v[150:153], v[126:129]
	v_mfma_f32_16x16x32_bf16 v[122:125], v[184:187], v[158:161], v[122:125]
	v_mfma_f32_16x16x32_bf16 v[118:121], v[192:195], v[150:153], v[118:121]
	v_mfma_f32_16x16x32_bf16 v[114:117], v[192:195], v[158:161], v[114:117]
	v_mfma_f32_16x16x32_bf16 v[110:113], v[200:203], v[150:153], v[110:113]
	v_mfma_f32_16x16x32_bf16 v[106:109], v[200:203], v[158:161], v[106:109]
	v_mfma_f32_16x16x32_bf16 v[102:105], v[208:211], v[150:153], v[102:105]
	v_mfma_f32_16x16x32_bf16 v[98:101], v[208:211], v[158:161], v[98:101]
	s_barrier
	s_add_i32 s58, s58, 2
	s_add_u32 s65, s50, s4
	s_addc_u32 s70, s51, s5
	s_add_u32 s66, s65, 0x100
	v_add_u32_e32 v144, s76, v142
	s_addc_u32 s67, s70, 0
	s_mov_b32 m0, s16
	ds_read_b128 v[212:215], v144
	ds_read_b128 v[216:219], v144 offset:1024
	ds_read_b128 v[220:223], v144 offset:2048
	ds_read_b128 v[224:227], v144 offset:3072
	s_nop 0
	v_lshl_add_u64 v[166:167], s[66:67], 0, v[0:1]
	global_load_lds_dwordx4 v[166:167], off
	v_lshl_add_u64 v[166:167], s[66:67], 0, v[140:141]
	s_mov_b32 m0, s17
	s_nop 0
	global_load_lds_dwordx4 v[166:167], off
	s_barrier
	s_waitcnt lgkmcnt(0)
	s_waitcnt lgkmcnt(0)
	v_mfma_f32_16x16x32_bf16 v[94:97], v[162:165], v[212:215], v[94:97]
	v_mfma_f32_16x16x32_bf16 v[90:93], v[162:165], v[220:223], v[90:93]
	v_mfma_f32_16x16x32_bf16 v[86:89], v[188:191], v[212:215], v[86:89]
	v_mfma_f32_16x16x32_bf16 v[82:85], v[188:191], v[220:223], v[82:85]
	v_mfma_f32_16x16x32_bf16 v[78:81], v[196:199], v[212:215], v[78:81]
	v_mfma_f32_16x16x32_bf16 v[74:77], v[196:199], v[220:223], v[74:77]
	v_mfma_f32_16x16x32_bf16 v[70:73], v[204:207], v[212:215], v[70:73]
	v_mfma_f32_16x16x32_bf16 v[66:69], v[204:207], v[220:223], v[66:69]
	v_mfma_f32_16x16x32_bf16 v[94:97], v[184:187], v[216:219], v[94:97]
	v_mfma_f32_16x16x32_bf16 v[90:93], v[184:187], v[224:227], v[90:93]
	v_mfma_f32_16x16x32_bf16 v[86:89], v[192:195], v[216:219], v[86:89]
	v_mfma_f32_16x16x32_bf16 v[82:85], v[192:195], v[224:227], v[82:85]
	v_mfma_f32_16x16x32_bf16 v[78:81], v[200:203], v[216:219], v[78:81]
	v_mfma_f32_16x16x32_bf16 v[74:77], v[200:203], v[224:227], v[74:77]
	v_mfma_f32_16x16x32_bf16 v[70:73], v[208:211], v[216:219], v[70:73]
	v_mfma_f32_16x16x32_bf16 v[66:69], v[208:211], v[224:227], v[66:69]
	s_barrier
	s_add_u32 s71, s44, s4
	s_addc_u32 s72, s45, s5
	s_add_u32 s66, s71, 0x100
	s_addc_u32 s67, s72, 0
	s_mov_b32 m0, s15
	ds_read_b128 v[162:165], v133 offset:16384
	ds_read_b128 v[184:187], v133 offset:17408
	ds_read_b128 v[188:191], v134 offset:16384
	ds_read_b128 v[192:195], v134 offset:17408
	ds_read_b128 v[196:199], v137 offset:16384
	ds_read_b128 v[200:203], v137 offset:17408
	ds_read_b128 v[204:207], v139 offset:16384
	ds_read_b128 v[208:211], v139 offset:17408
	s_nop 0
	v_lshl_add_u64 v[166:167], s[66:67], 0, v[0:1]
	global_load_lds_dwordx4 v[166:167], off
	v_lshl_add_u64 v[166:167], s[66:67], 0, v[140:141]
	s_mov_b32 m0, s18
	s_nop 0
	global_load_lds_dwordx4 v[166:167], off
	s_barrier
	s_waitcnt lgkmcnt(0)
	s_waitcnt lgkmcnt(0)
	v_mfma_f32_16x16x32_bf16 v[62:65], v[162:165], v[146:149], v[62:65]
	v_mfma_f32_16x16x32_bf16 v[58:61], v[162:165], v[154:157], v[58:61]
	v_mfma_f32_16x16x32_bf16 v[54:57], v[188:191], v[146:149], v[54:57]
	v_mfma_f32_16x16x32_bf16 v[50:53], v[188:191], v[154:157], v[50:53]
	v_mfma_f32_16x16x32_bf16 v[46:49], v[196:199], v[146:149], v[46:49]
	v_mfma_f32_16x16x32_bf16 v[42:45], v[196:199], v[154:157], v[42:45]
	v_mfma_f32_16x16x32_bf16 v[38:41], v[204:207], v[146:149], v[38:41]
	v_mfma_f32_16x16x32_bf16 v[34:37], v[204:207], v[154:157], v[34:37]
	v_mfma_f32_16x16x32_bf16 v[62:65], v[184:187], v[150:153], v[62:65]
	v_mfma_f32_16x16x32_bf16 v[58:61], v[184:187], v[158:161], v[58:61]
	v_mfma_f32_16x16x32_bf16 v[54:57], v[192:195], v[150:153], v[54:57]
	v_mfma_f32_16x16x32_bf16 v[50:53], v[192:195], v[158:161], v[50:53]
	v_mfma_f32_16x16x32_bf16 v[46:49], v[200:203], v[150:153], v[46:49]
	v_mfma_f32_16x16x32_bf16 v[42:45], v[200:203], v[158:161], v[42:45]
	v_mfma_f32_16x16x32_bf16 v[38:41], v[208:211], v[150:153], v[38:41]
	v_mfma_f32_16x16x32_bf16 v[34:37], v[208:211], v[158:161], v[34:37]
	s_barrier
; #define LDA(dst, b, h) for (int m = 0; m < 4; ++m) for (int k = 0; k < 2; ++k) \
;     dst[m][k] = *reinterpret_cast<const bf16x8*>((char*)SA(b, h) + lds_byte(wr * 64 + m * 16 + fr, k * 32 + fq * 8))
; #define LDB(dst, b, h) for (int n = 0; n < 2; ++n) for (int k = 0; k < 2; ++k) \
;     dst[n][k] = *reinterpret_cast<const bf16x8*>((char*)SB(b, h) + lds_byte(wc * 32 + n * 16 + fr, k * 32 + fq * 8))
; #define MMA(ai, bj, At, Bt_) do { __builtin_amdgcn_s_setprio(1); \
;     for (int m = 0; m < 4; ++m) for (int n = 0; n < 2; ++n) for (int k = 0; k < 2; ++k) \
;       acc[ai][bj][m][n] = __builtin_amdgcn_mfma_f32_16x16x32_bf16(At[m][k], Bt_[n][k], acc[ai][bj][m][n], 0, 0, 0); \
;     __builtin_amdgcn_s_setprio(0); } while (0)
; #define WAIT_V(n) asm volatile("s_waitcnt vmcnt(" #n ")" ::: "memory")
; #define WAIT_L(n) asm volatile("s_waitcnt lgkmcnt(" #n ")" ::: "memory")
; #define BAR __builtin_amdgcn_s_barrier()
; #define SCHED __builtin_amdgcn_sched_barrier(0)
;     ...
;       STAGE(SB(0, 1), Bt, bcol + HALF, t + 2);
;       WAIT_V(6); BAR; MMA(1, 1, At, B1); BAR;
;       LDB(B0, 1, 0); SCHED; LDA(At, 1, 0); STAGE(SA(0, 1), A, brow + HALF, t + 2);
;       WAIT_L(8); BAR; WAIT_L(0); MMA(0, 0, At, B0); BAR; SCHED;
;       LDB(B1, 1, 1); STAGE(SB(1, 0), Bt, bcol, t + 3);
;       BAR; WAIT_L(0); MMA(0, 1, At, B1); BAR;
;       LDA(At, 1, 1); STAGE(SA(1, 0), A, brow, t + 3);
	s_add_u32 s73, s6, s4
	s_addc_u32 s82, s7, s5
	s_add_u32 s66, s73, 0x160100
	s_addc_u32 s67, s82, 0
	s_mov_b32 m0, s19
	s_nop 0
	v_lshl_add_u64 v[146:147], s[66:67], 0, v[0:1]
	global_load_lds_dwordx4 v[146:147], off
	v_lshl_add_u64 v[146:147], s[66:67], 0, v[140:141]
	s_mov_b32 m0, s21
	s_nop 0
	global_load_lds_dwordx4 v[146:147], off
	s_waitcnt vmcnt(6)
	s_barrier
	v_mfma_f32_16x16x32_bf16 v[30:33], v[162:165], v[212:215], v[30:33]
	v_mfma_f32_16x16x32_bf16 v[26:29], v[162:165], v[220:223], v[26:29]
	v_mfma_f32_16x16x32_bf16 v[22:25], v[188:191], v[212:215], v[22:25]
	v_mfma_f32_16x16x32_bf16 v[18:21], v[188:191], v[220:223], v[18:21]
	v_mfma_f32_16x16x32_bf16 v[14:17], v[196:199], v[212:215], v[14:17]
	v_mfma_f32_16x16x32_bf16 v[10:13], v[196:199], v[220:223], v[10:13]
	v_mfma_f32_16x16x32_bf16 v[6:9], v[204:207], v[212:215], v[6:9]
	v_mfma_f32_16x16x32_bf16 v[2:5], v[204:207], v[220:223], v[2:5]
	v_mfma_f32_16x16x32_bf16 v[30:33], v[184:187], v[216:219], v[30:33]
	v_mfma_f32_16x16x32_bf16 v[26:29], v[184:187], v[224:227], v[26:29]
	v_mfma_f32_16x16x32_bf16 v[22:25], v[192:195], v[216:219], v[22:25]
	v_mfma_f32_16x16x32_bf16 v[18:21], v[192:195], v[224:227], v[18:21]
	v_mfma_f32_16x16x32_bf16 v[14:17], v[200:203], v[216:219], v[14:17]
	v_mfma_f32_16x16x32_bf16 v[10:13], v[200:203], v[224:227], v[10:13]
	v_mfma_f32_16x16x32_bf16 v[6:9], v[208:211], v[216:219], v[6:9]
	v_mfma_f32_16x16x32_bf16 v[2:5], v[208:211], v[224:227], v[2:5]
	s_barrier
	v_add_u32_e32 v145, s77, v142
	ds_read_b128 v[148:151], v145
	ds_read_b128 v[152:155], v145 offset:1024
	ds_read_b128 v[156:159], v145 offset:2048
	ds_read_b128 v[160:163], v145 offset:3072
	s_add_u32 s66, s71, 0x160100
	s_addc_u32 s67, s72, 0
	s_mov_b32 m0, s30
	ds_read_b128 v[164:167], v133 offset:32768
	ds_read_b128 v[184:187], v133 offset:33792
	ds_read_b128 v[188:191], v134 offset:32768
	ds_read_b128 v[192:195], v134 offset:33792
	ds_read_b128 v[196:199], v137 offset:32768
	ds_read_b128 v[200:203], v137 offset:33792
	ds_read_b128 v[204:207], v139 offset:32768
	ds_read_b128 v[208:211], v139 offset:33792
	s_nop 0
	v_lshl_add_u64 v[146:147], s[66:67], 0, v[0:1]
	global_load_lds_dwordx4 v[146:147], off
	v_lshl_add_u64 v[146:147], s[66:67], 0, v[140:141]
	s_mov_b32 m0, s31
	s_nop 0
	global_load_lds_dwordx4 v[146:147], off
	s_waitcnt lgkmcnt(8)
	s_barrier
	s_waitcnt lgkmcnt(0)
	s_waitcnt lgkmcnt(0)
	v_mfma_f32_16x16x32_bf16 v[126:129], v[164:167], v[148:151], v[126:129]
	v_mfma_f32_16x16x32_bf16 v[122:125], v[164:167], v[156:159], v[122:125]
	v_mfma_f32_16x16x32_bf16 v[118:121], v[188:191], v[148:151], v[118:121]
	v_mfma_f32_16x16x32_bf16 v[114:117], v[188:191], v[156:159], v[114:117]
	v_mfma_f32_16x16x32_bf16 v[110:113], v[196:199], v[148:151], v[110:113]
	v_mfma_f32_16x16x32_bf16 v[106:109], v[196:199], v[156:159], v[106:109]
	v_mfma_f32_16x16x32_bf16 v[102:105], v[204:207], v[148:151], v[102:105]
	v_mfma_f32_16x16x32_bf16 v[98:101], v[204:207], v[156:159], v[98:101]
	v_mfma_f32_16x16x32_bf16 v[126:129], v[184:187], v[152:155], v[126:129]
	v_mfma_f32_16x16x32_bf16 v[122:125], v[184:187], v[160:163], v[122:125]
	v_mfma_f32_16x16x32_bf16 v[118:121], v[192:195], v[152:155], v[118:121]
	v_mfma_f32_16x16x32_bf16 v[114:117], v[192:195], v[160:163], v[114:117]
	v_mfma_f32_16x16x32_bf16 v[110:113], v[200:203], v[152:155], v[110:113]
	v_mfma_f32_16x16x32_bf16 v[106:109], v[200:203], v[160:163], v[106:109]
	v_mfma_f32_16x16x32_bf16 v[102:105], v[208:211], v[152:155], v[102:105]
	v_mfma_f32_16x16x32_bf16 v[98:101], v[208:211], v[160:163], v[98:101]
	s_barrier
	s_add_u32 s66, s65, 0x180
	v_add_u32_e32 v146, s78, v142
	s_addc_u32 s67, s70, 0
	s_mov_b32 m0, s34
	ds_read_b128 v[212:215], v146
	ds_read_b128 v[216:219], v146 offset:1024
	ds_read_b128 v[220:223], v146 offset:2048
	ds_read_b128 v[224:227], v146 offset:3072
	s_nop 0
	v_lshl_add_u64 v[228:229], s[66:67], 0, v[0:1]
	global_load_lds_dwordx4 v[228:229], off
	v_lshl_add_u64 v[228:229], s[66:67], 0, v[140:141]
	s_mov_b32 m0, s35
	s_nop 0
	global_load_lds_dwordx4 v[228:229], off
	s_barrier
	s_waitcnt lgkmcnt(0)
	s_waitcnt lgkmcnt(0)
	v_mfma_f32_16x16x32_bf16 v[94:97], v[164:167], v[212:215], v[94:97]
	v_mfma_f32_16x16x32_bf16 v[90:93], v[164:167], v[220:223], v[90:93]
	v_mfma_f32_16x16x32_bf16 v[86:89], v[188:191], v[212:215], v[86:89]
	v_mfma_f32_16x16x32_bf16 v[82:85], v[188:191], v[220:223], v[82:85]
	v_mfma_f32_16x16x32_bf16 v[78:81], v[196:199], v[212:215], v[78:81]
	v_mfma_f32_16x16x32_bf16 v[74:77], v[196:199], v[220:223], v[74:77]
	v_mfma_f32_16x16x32_bf16 v[70:73], v[204:207], v[212:215], v[70:73]
	v_mfma_f32_16x16x32_bf16 v[66:69], v[204:207], v[220:223], v[66:69]
	v_mfma_f32_16x16x32_bf16 v[94:97], v[184:187], v[216:219], v[94:97]
	v_mfma_f32_16x16x32_bf16 v[90:93], v[184:187], v[224:227], v[90:93]
	v_mfma_f32_16x16x32_bf16 v[86:89], v[192:195], v[216:219], v[86:89]
	v_mfma_f32_16x16x32_bf16 v[82:85], v[192:195], v[224:227], v[82:85]
	v_mfma_f32_16x16x32_bf16 v[78:81], v[200:203], v[216:219], v[78:81]
	v_mfma_f32_16x16x32_bf16 v[74:77], v[200:203], v[224:227], v[74:77]
	v_mfma_f32_16x16x32_bf16 v[70:73], v[208:211], v[216:219], v[70:73]
	v_mfma_f32_16x16x32_bf16 v[66:69], v[208:211], v[224:227], v[66:69]
	s_barrier
	s_add_u32 s66, s71, 0x180
	s_addc_u32 s67, s72, 0
	s_mov_b32 m0, s37
	ds_read_b128 v[164:167], v133 offset:49152
	ds_read_b128 v[184:187], v133 offset:50176
	ds_read_b128 v[188:191], v134 offset:49152
	ds_read_b128 v[192:195], v134 offset:50176
	ds_read_b128 v[196:199], v137 offset:49152
	ds_read_b128 v[200:203], v137 offset:50176
	ds_read_b128 v[204:207], v139 offset:49152
	ds_read_b128 v[208:211], v139 offset:50176
	s_nop 0
	v_lshl_add_u64 v[228:229], s[66:67], 0, v[0:1]
	global_load_lds_dwordx4 v[228:229], off
	v_lshl_add_u64 v[228:229], s[66:67], 0, v[140:141]
	s_mov_b32 m0, s38
	s_nop 0
	global_load_lds_dwordx4 v[228:229], off
	s_barrier
; #define LDA(dst, b, h) for (int m = 0; m < 4; ++m) for (int k = 0; k < 2; ++k) \
;     dst[m][k] = *reinterpret_cast<const bf16x8*>((char*)SA(b, h) + lds_byte(wr * 64 + m * 16 + fr, k * 32 + fq * 8))
; #define LDB(dst, b, h) for (int n = 0; n < 2; ++n) for (int k = 0; k < 2; ++k) \
;     dst[n][k] = *reinterpret_cast<const bf16x8*>((char*)SB(b, h) + lds_byte(wc * 32 + n * 16 + fr, k * 32 + fq * 8))
; #define MMA(ai, bj, At, Bt_) do { __builtin_amdgcn_s_setprio(1); \
;     for (int m = 0; m < 4; ++m) for (int n = 0; n < 2; ++n) for (int k = 0; k < 2; ++k) \
;       acc[ai][bj][m][n] = __builtin_amdgcn_mfma_f32_16x16x32_bf16(At[m][k], Bt_[n][k], acc[ai][bj][m][n], 0, 0, 0); \
;     __builtin_amdgcn_s_setprio(0); } while (0)
; #define WAIT_V(n) asm volatile("s_waitcnt vmcnt(" #n ")" ::: "memory")
; #define WAIT_L(n) asm volatile("s_waitcnt lgkmcnt(" #n ")" ::: "memory")
; #define BAR __builtin_amdgcn_s_barrier()
; #define SCHED __builtin_amdgcn_sched_barrier(0)
;     ...
;       BAR; WAIT_L(0); MMA(1, 0, At, B0); BAR; SCHED;
;       STAGE(SB(1, 1), Bt, bcol + HALF, t + 3);
;       WAIT_V(6); BAR; MMA(1, 1, At, B1); BAR;
;     }
;     { LDB(B0, 0, 0); LDA(At, 0, 0); STAGE(SA(1, 1), A, brow + HALF, nt - 1);
;       BAR; WAIT_L(0); MMA(0, 0, At, B0); BAR;
;       LDB(B1, 0, 1); BAR; WAIT_L(0); MMA(0, 1, At, B1); BAR;
	s_waitcnt lgkmcnt(0)
	s_waitcnt lgkmcnt(0)
	v_mfma_f32_16x16x32_bf16 v[62:65], v[164:167], v[148:151], v[62:65]
	v_mfma_f32_16x16x32_bf16 v[58:61], v[164:167], v[156:159], v[58:61]
	v_mfma_f32_16x16x32_bf16 v[54:57], v[188:191], v[148:151], v[54:57]
	v_mfma_f32_16x16x32_bf16 v[50:53], v[188:191], v[156:159], v[50:53]
	v_mfma_f32_16x16x32_bf16 v[46:49], v[196:199], v[148:151], v[46:49]
	v_mfma_f32_16x16x32_bf16 v[42:45], v[196:199], v[156:159], v[42:45]
	v_mfma_f32_16x16x32_bf16 v[38:41], v[204:207], v[148:151], v[38:41]
	v_mfma_f32_16x16x32_bf16 v[34:37], v[204:207], v[156:159], v[34:37]
	v_mfma_f32_16x16x32_bf16 v[62:65], v[184:187], v[152:155], v[62:65]
	v_mfma_f32_16x16x32_bf16 v[58:61], v[184:187], v[160:163], v[58:61]
	v_mfma_f32_16x16x32_bf16 v[54:57], v[192:195], v[152:155], v[54:57]
	v_mfma_f32_16x16x32_bf16 v[50:53], v[192:195], v[160:163], v[50:53]
	v_mfma_f32_16x16x32_bf16 v[46:49], v[200:203], v[152:155], v[46:49]
	v_mfma_f32_16x16x32_bf16 v[42:45], v[200:203], v[160:163], v[42:45]
	v_mfma_f32_16x16x32_bf16 v[38:41], v[208:211], v[152:155], v[38:41]
	v_mfma_f32_16x16x32_bf16 v[34:37], v[208:211], v[160:163], v[34:37]
	s_barrier
	s_add_u32 s66, s73, 0x160180
	s_addc_u32 s67, s82, 0
	s_mov_b32 m0, s41
	s_nop 0
	v_lshl_add_u64 v[148:149], s[66:67], 0, v[0:1]
	global_load_lds_dwordx4 v[148:149], off
	v_lshl_add_u64 v[148:149], s[66:67], 0, v[140:141]
	s_mov_b32 m0, s42
	s_nop 0
	global_load_lds_dwordx4 v[148:149], off
	s_add_u32 s6, s6, 0x100
	s_addc_u32 s7, s7, 0
	s_add_u32 s44, s44, 0x100
	s_addc_u32 s45, s45, 0
	s_add_u32 s50, s50, 0x100
	s_addc_u32 s51, s51, 0
	s_add_u32 s55, s55, 0x100
	s_addc_u32 s57, s57, 0
	s_cmp_ge_u32 s58, s43
	s_waitcnt vmcnt(6)
	s_barrier
	v_mfma_f32_16x16x32_bf16 v[30:33], v[164:167], v[212:215], v[30:33]
	v_mfma_f32_16x16x32_bf16 v[26:29], v[164:167], v[220:223], v[26:29]
	v_mfma_f32_16x16x32_bf16 v[22:25], v[188:191], v[212:215], v[22:25]
	v_mfma_f32_16x16x32_bf16 v[18:21], v[188:191], v[220:223], v[18:21]
	v_mfma_f32_16x16x32_bf16 v[14:17], v[196:199], v[212:215], v[14:17]
	v_mfma_f32_16x16x32_bf16 v[10:13], v[196:199], v[220:223], v[10:13]
	v_mfma_f32_16x16x32_bf16 v[6:9], v[204:207], v[212:215], v[6:9]
	v_mfma_f32_16x16x32_bf16 v[2:5], v[204:207], v[220:223], v[2:5]
	v_mfma_f32_16x16x32_bf16 v[30:33], v[184:187], v[216:219], v[30:33]
	v_mfma_f32_16x16x32_bf16 v[26:29], v[184:187], v[224:227], v[26:29]
	v_mfma_f32_16x16x32_bf16 v[22:25], v[192:195], v[216:219], v[22:25]
	v_mfma_f32_16x16x32_bf16 v[18:21], v[192:195], v[224:227], v[18:21]
	v_mfma_f32_16x16x32_bf16 v[14:17], v[200:203], v[216:219], v[14:17]
	v_mfma_f32_16x16x32_bf16 v[10:13], v[200:203], v[224:227], v[10:13]
	v_mfma_f32_16x16x32_bf16 v[6:9], v[208:211], v[216:219], v[6:9]
	v_mfma_f32_16x16x32_bf16 v[2:5], v[208:211], v[224:227], v[2:5]
	s_barrier
	s_cbranch_scc0 .LBB0_98
	s_add_i32 s4, s48, s14
	s_add_i32 s48, s4, -1
	s_lshl_b64 s[4:5], s[48:49], 7
	s_add_u32 s4, s22, s4
	s_addc_u32 s5, s23, s5
	s_add_u32 s4, s4, s40
	s_addc_u32 s5, s5, s39
	s_mov_b32 m0, s63
	ds_read_b128 v[148:151], v143
	ds_read_b128 v[152:155], v143 offset:1024
	ds_read_b128 v[156:159], v143 offset:2048
	ds_read_b128 v[160:163], v143 offset:3072
	ds_read_b128 v[164:167], v133
	ds_read_b128 v[184:187], v133 offset:1024
	ds_read_b128 v[188:191], v134
	ds_read_b128 v[192:195], v134 offset:1024
	ds_read_b128 v[196:199], v137
	ds_read_b128 v[200:203], v137 offset:1024
	ds_read_b128 v[204:207], v139
	ds_read_b128 v[208:211], v139 offset:1024
	s_nop 0
	v_lshl_add_u64 v[142:143], s[4:5], 0, v[0:1]
	global_load_lds_dwordx4 v[142:143], off
	v_lshl_add_u64 v[140:141], s[4:5], 0, v[140:141]
	s_mov_b32 m0, s59
	s_nop 0
	global_load_lds_dwordx4 v[140:141], off
	s_barrier
	s_waitcnt lgkmcnt(0)
	s_waitcnt lgkmcnt(0)
	v_mfma_f32_16x16x32_bf16 v[126:129], v[164:167], v[148:151], v[126:129]
	v_mfma_f32_16x16x32_bf16 v[122:125], v[164:167], v[156:159], v[122:125]
	v_mfma_f32_16x16x32_bf16 v[118:121], v[188:191], v[148:151], v[118:121]
	v_mfma_f32_16x16x32_bf16 v[110:113], v[196:199], v[148:151], v[110:113]
	v_mfma_f32_16x16x32_bf16 v[106:109], v[196:199], v[156:159], v[106:109]
	v_mfma_f32_16x16x32_bf16 v[102:105], v[204:207], v[148:151], v[102:105]
	v_mfma_f32_16x16x32_bf16 v[98:101], v[204:207], v[156:159], v[98:101]
	v_mfma_f32_16x16x32_bf16 v[126:129], v[184:187], v[152:155], v[126:129]
	v_mfma_f32_16x16x32_bf16 v[122:125], v[184:187], v[160:163], v[122:125]
	v_mfma_f32_16x16x32_bf16 v[118:121], v[192:195], v[152:155], v[118:121]
	v_mfma_f32_16x16x32_bf16 v[114:117], v[188:191], v[156:159], v[114:117]
	v_mfma_f32_16x16x32_bf16 v[110:113], v[200:203], v[152:155], v[110:113]
	v_mfma_f32_16x16x32_bf16 v[106:109], v[200:203], v[160:163], v[106:109]
	v_mfma_f32_16x16x32_bf16 v[102:105], v[208:211], v[152:155], v[102:105]
	v_mfma_f32_16x16x32_bf16 v[98:101], v[208:211], v[160:163], v[98:101]
	v_mfma_f32_16x16x32_bf16 v[140:143], v[192:195], v[160:163], v[114:117]
	s_barrier
	s_nop 0
	ds_read_b128 v[114:117], v144
	ds_read_b128 v[212:215], v144 offset:1024
	ds_read_b128 v[216:219], v144 offset:2048
	ds_read_b128 v[220:223], v144 offset:3072
	s_barrier
; #define LDA(dst, b, h) for (int m = 0; m < 4; ++m) for (int k = 0; k < 2; ++k) \
;     dst[m][k] = *reinterpret_cast<const bf16x8*>((char*)SA(b, h) + lds_byte(wr * 64 + m * 16 + fr, k * 32 + fq * 8))
; #define LDB(dst, b, h) for (int n = 0; n < 2; ++n) for (int k = 0; k < 2; ++k) \
;     dst[n][k] = *reinterpret_cast<const bf16x8*>((char*)SB(b, h) + lds_byte(wc * 32 + n * 16 + fr, k * 32 + fq * 8))
; #define MMA(ai, bj, At, Bt_) do { __builtin_amdgcn_s_setprio(1); \
;     for (int m = 0; m < 4; ++m) for (int n = 0; n < 2; ++n) for (int k = 0; k < 2; ++k) \
;       acc[ai][bj][m][n] = __builtin_amdgcn_mfma_f32_16x16x32_bf16(At[m][k], Bt_[n][k], acc[ai][bj][m][n], 0, 0, 0); \
;     __builtin_amdgcn_s_setprio(0); } while (0)
; #define WAIT_V(n) asm volatile("s_waitcnt vmcnt(" #n ")" ::: "memory")
; #define WAIT_L(n) asm volatile("s_waitcnt lgkmcnt(" #n ")" ::: "memory")
; #define BAR __builtin_amdgcn_s_barrier()
;     ...
;       LDB(B1, 0, 1); BAR; WAIT_L(0); MMA(0, 1, At, B1); BAR;
;       LDA(At, 0, 1); WAIT_V(4); BAR; WAIT_L(0); MMA(1, 0, At, B0); MMA(1, 1, At, B1); BAR; }
;     { LDB(B0, 1, 0); LDA(At, 1, 0); WAIT_V(2); BAR; WAIT_L(0); MMA(0, 0, At, B0); BAR;
	s_waitcnt lgkmcnt(0)
	s_waitcnt lgkmcnt(0)
	v_mfma_f32_16x16x32_bf16 v[90:93], v[164:167], v[216:219], v[90:93]
	v_mfma_f32_16x16x32_bf16 v[86:89], v[188:191], v[114:117], v[86:89]
	v_mfma_f32_16x16x32_bf16 v[94:97], v[164:167], v[114:117], v[94:97]
	v_mfma_f32_16x16x32_bf16 v[90:93], v[184:187], v[220:223], v[90:93]
	v_mfma_f32_16x16x32_bf16 v[86:89], v[192:195], v[212:215], v[86:89]
	v_mfma_f32_16x16x32_bf16 v[82:85], v[188:191], v[216:219], v[82:85]
	v_mfma_f32_16x16x32_bf16 v[78:81], v[196:199], v[114:117], v[78:81]
	v_mfma_f32_16x16x32_bf16 v[74:77], v[196:199], v[216:219], v[74:77]
	v_mfma_f32_16x16x32_bf16 v[70:73], v[204:207], v[114:117], v[70:73]
	v_mfma_f32_16x16x32_bf16 v[66:69], v[204:207], v[216:219], v[66:69]
	v_mfma_f32_16x16x32_bf16 v[224:227], v[184:187], v[212:215], v[94:97]
	v_mfma_f32_16x16x32_bf16 v[164:167], v[192:195], v[220:223], v[82:85]
	v_mfma_f32_16x16x32_bf16 v[184:187], v[200:203], v[212:215], v[78:81]
	v_mfma_f32_16x16x32_bf16 v[188:191], v[200:203], v[220:223], v[74:77]
	v_mfma_f32_16x16x32_bf16 v[192:195], v[208:211], v[212:215], v[70:73]
	v_mfma_f32_16x16x32_bf16 v[196:199], v[208:211], v[220:223], v[66:69]
	s_barrier
	s_nop 0
	ds_read_b128 v[66:69], v133 offset:16384
	ds_read_b128 v[70:73], v133 offset:17408
	ds_read_b128 v[74:77], v134 offset:16384
	ds_read_b128 v[78:81], v134 offset:17408
	ds_read_b128 v[82:85], v137 offset:16384
	ds_read_b128 v[94:97], v137 offset:17408
	ds_read_b128 v[200:203], v139 offset:16384
	ds_read_b128 v[204:207], v139 offset:17408
	s_waitcnt vmcnt(4)
	s_barrier
	s_waitcnt lgkmcnt(0)
	s_waitcnt lgkmcnt(0)
	v_mfma_f32_16x16x32_bf16 v[62:65], v[66:69], v[148:151], v[62:65]
	v_mfma_f32_16x16x32_bf16 v[58:61], v[66:69], v[156:159], v[58:61]
	v_mfma_f32_16x16x32_bf16 v[54:57], v[74:77], v[148:151], v[54:57]
	v_mfma_f32_16x16x32_bf16 v[50:53], v[74:77], v[156:159], v[50:53]
	v_mfma_f32_16x16x32_bf16 v[46:49], v[82:85], v[148:151], v[46:49]
	v_mfma_f32_16x16x32_bf16 v[42:45], v[82:85], v[156:159], v[42:45]
	v_mfma_f32_16x16x32_bf16 v[38:41], v[200:203], v[148:151], v[38:41]
	v_mfma_f32_16x16x32_bf16 v[34:37], v[200:203], v[156:159], v[34:37]
	v_mfma_f32_16x16x32_bf16 v[62:65], v[70:73], v[152:155], v[62:65]
	v_mfma_f32_16x16x32_bf16 v[58:61], v[70:73], v[160:163], v[58:61]
	v_mfma_f32_16x16x32_bf16 v[54:57], v[78:81], v[152:155], v[54:57]
	v_mfma_f32_16x16x32_bf16 v[50:53], v[78:81], v[160:163], v[50:53]
	v_mfma_f32_16x16x32_bf16 v[46:49], v[94:97], v[152:155], v[46:49]
	v_mfma_f32_16x16x32_bf16 v[42:45], v[94:97], v[160:163], v[42:45]
	v_mfma_f32_16x16x32_bf16 v[38:41], v[204:207], v[152:155], v[38:41]
	v_mfma_f32_16x16x32_bf16 v[34:37], v[204:207], v[160:163], v[34:37]
	v_mfma_f32_16x16x32_bf16 v[30:33], v[66:69], v[114:117], v[30:33]
	v_mfma_f32_16x16x32_bf16 v[26:29], v[66:69], v[216:219], v[26:29]
	v_mfma_f32_16x16x32_bf16 v[22:25], v[74:77], v[114:117], v[22:25]
	v_mfma_f32_16x16x32_bf16 v[18:21], v[74:77], v[216:219], v[18:21]
	v_mfma_f32_16x16x32_bf16 v[14:17], v[82:85], v[114:117], v[14:17]
	v_mfma_f32_16x16x32_bf16 v[10:13], v[82:85], v[216:219], v[10:13]
	v_mfma_f32_16x16x32_bf16 v[6:9], v[200:203], v[114:117], v[6:9]
	v_mfma_f32_16x16x32_bf16 v[2:5], v[200:203], v[216:219], v[2:5]
	v_mfma_f32_16x16x32_bf16 v[148:151], v[70:73], v[212:215], v[30:33]
	v_mfma_f32_16x16x32_bf16 v[152:155], v[70:73], v[220:223], v[26:29]
	v_mfma_f32_16x16x32_bf16 v[156:159], v[78:81], v[212:215], v[22:25]
	v_mfma_f32_16x16x32_bf16 v[160:163], v[78:81], v[220:223], v[18:21]
	v_mfma_f32_16x16x32_bf16 v[208:211], v[94:97], v[212:215], v[14:17]
	v_mfma_f32_16x16x32_bf16 v[228:231], v[94:97], v[220:223], v[10:13]
	v_mfma_f32_16x16x32_bf16 v[212:215], v[204:207], v[212:215], v[6:9]
	v_mfma_f32_16x16x32_bf16 v[200:203], v[204:207], v[220:223], v[2:5]
	s_barrier
	ds_read_b128 v[14:17], v145
	ds_read_b128 v[30:33], v145 offset:1024
	ds_read_b128 v[204:207], v145 offset:2048
	ds_read_b128 v[216:219], v145 offset:3072
	ds_read_b128 v[2:5], v133 offset:32768
	ds_read_b128 v[6:9], v133 offset:33792
	ds_read_b128 v[10:13], v134 offset:32768
	ds_read_b128 v[18:21], v134 offset:33792
	ds_read_b128 v[22:25], v137 offset:32768
	ds_read_b128 v[26:29], v137 offset:33792
	ds_read_b128 v[220:223], v139 offset:32768
	ds_read_b128 v[232:235], v139 offset:33792
	s_waitcnt vmcnt(2)
	s_barrier
; #define LDA(dst, b, h) for (int m = 0; m < 4; ++m) for (int k = 0; k < 2; ++k) \
;     dst[m][k] = *reinterpret_cast<const bf16x8*>((char*)SA(b, h) + lds_byte(wr * 64 + m * 16 + fr, k * 32 + fq * 8))
; #define LDB(dst, b, h) for (int n = 0; n < 2; ++n) for (int k = 0; k < 2; ++k) \
;     dst[n][k] = *reinterpret_cast<const bf16x8*>((char*)SB(b, h) + lds_byte(wc * 32 + n * 16 + fr, k * 32 + fq * 8))
; #define MMA(ai, bj, At, Bt_) do { __builtin_amdgcn_s_setprio(1); \
;     for (int m = 0; m < 4; ++m) for (int n = 0; n < 2; ++n) for (int k = 0; k < 2; ++k) \
;       acc[ai][bj][m][n] = __builtin_amdgcn_mfma_f32_16x16x32_bf16(At[m][k], Bt_[n][k], acc[ai][bj][m][n], 0, 0, 0); \
;     __builtin_amdgcn_s_setprio(0); } while (0)
; #define WAIT_V(n) asm volatile("s_waitcnt vmcnt(" #n ")" ::: "memory")
; #define WAIT_L(n) asm volatile("s_waitcnt lgkmcnt(" #n ")" ::: "memory")
; #define BAR __builtin_amdgcn_s_barrier()
;     ...
;     { LDB(B0, 1, 0); LDA(At, 1, 0); WAIT_V(2); BAR; WAIT_L(0); MMA(0, 0, At, B0); BAR;
;       LDB(B1, 1, 1); WAIT_V(0); BAR; WAIT_L(0); MMA(0, 1, At, B1); BAR;
;       LDA(At, 1, 1); BAR; WAIT_L(0); MMA(1, 0, At, B0); MMA(1, 1, At, B1); BAR; }
;     if (wr == 0) BAR;
	s_waitcnt lgkmcnt(0)
	s_waitcnt lgkmcnt(0)
	v_mfma_f32_16x16x32_bf16 v[66:69], v[2:5], v[14:17], v[126:129]
	v_mfma_f32_16x16x32_bf16 v[114:117], v[6:9], v[30:33], v[66:69]
	v_mfma_f32_16x16x32_bf16 v[66:69], v[2:5], v[204:207], v[122:125]
	v_mfma_f32_16x16x32_bf16 v[126:129], v[6:9], v[216:219], v[66:69]
	v_mfma_f32_16x16x32_bf16 v[66:69], v[10:13], v[14:17], v[118:121]
	v_mfma_f32_16x16x32_bf16 v[82:85], v[18:21], v[30:33], v[66:69]
	v_mfma_f32_16x16x32_bf16 v[66:69], v[10:13], v[204:207], v[140:143]
	v_mfma_f32_16x16x32_bf16 v[94:97], v[18:21], v[216:219], v[66:69]
	v_mfma_f32_16x16x32_bf16 v[66:69], v[22:25], v[14:17], v[110:113]
	v_mfma_f32_16x16x32_bf16 v[74:77], v[26:29], v[30:33], v[66:69]
	v_mfma_f32_16x16x32_bf16 v[66:69], v[22:25], v[204:207], v[106:109]
	v_mfma_f32_16x16x32_bf16 v[78:81], v[26:29], v[216:219], v[66:69]
	v_mfma_f32_16x16x32_bf16 v[66:69], v[220:223], v[14:17], v[102:105]
	v_mfma_f32_16x16x32_bf16 v[70:73], v[220:223], v[204:207], v[98:101]
	v_mfma_f32_16x16x32_bf16 v[66:69], v[232:235], v[30:33], v[66:69]
	v_mfma_f32_16x16x32_bf16 v[70:73], v[232:235], v[216:219], v[70:73]
	s_barrier
	ds_read_b128 v[140:143], v146
	ds_read_b128 v[236:239], v146 offset:1024
	ds_read_b128 v[240:243], v146 offset:2048
	ds_read_b128 v[144:147], v146 offset:3072
	s_waitcnt vmcnt(0)
	s_barrier
	s_waitcnt lgkmcnt(0)
	s_waitcnt lgkmcnt(0)
	v_mfma_f32_16x16x32_bf16 v[98:101], v[2:5], v[140:143], v[224:227]
	v_mfma_f32_16x16x32_bf16 v[2:5], v[2:5], v[240:243], v[90:93]
	v_mfma_f32_16x16x32_bf16 v[118:121], v[6:9], v[144:147], v[2:5]
	v_mfma_f32_16x16x32_bf16 v[2:5], v[10:13], v[140:143], v[86:89]
	v_mfma_f32_16x16x32_bf16 v[102:105], v[18:21], v[236:239], v[2:5]
	v_mfma_f32_16x16x32_bf16 v[2:5], v[10:13], v[240:243], v[164:167]
	v_mfma_f32_16x16x32_bf16 v[122:125], v[18:21], v[144:147], v[2:5]
	v_mfma_f32_16x16x32_bf16 v[2:5], v[22:25], v[140:143], v[184:187]
	v_mfma_f32_16x16x32_bf16 v[90:93], v[26:29], v[236:239], v[2:5]
	v_mfma_f32_16x16x32_bf16 v[2:5], v[22:25], v[240:243], v[188:191]
	v_mfma_f32_16x16x32_bf16 v[110:113], v[26:29], v[144:147], v[2:5]
	v_mfma_f32_16x16x32_bf16 v[2:5], v[220:223], v[140:143], v[192:195]
	v_mfma_f32_16x16x32_bf16 v[86:89], v[232:235], v[236:239], v[2:5]
	v_mfma_f32_16x16x32_bf16 v[2:5], v[220:223], v[240:243], v[196:199]
	v_mfma_f32_16x16x32_bf16 v[98:101], v[6:9], v[236:239], v[98:101]
	v_mfma_f32_16x16x32_bf16 v[106:109], v[232:235], v[144:147], v[2:5]
	s_barrier
	ds_read_b128 v[164:167], v133 offset:49152
	ds_read_b128 v[184:187], v133 offset:50176
	ds_read_b128 v[188:191], v134 offset:49152
	ds_read_b128 v[192:195], v134 offset:50176
	ds_read_b128 v[196:199], v137 offset:49152
	ds_read_b128 v[220:223], v137 offset:50176
	ds_read_b128 v[224:227], v139 offset:49152
	ds_read_b128 v[232:235], v139 offset:50176
	s_barrier
	s_waitcnt lgkmcnt(0)
	s_waitcnt lgkmcnt(0)
	v_mfma_f32_16x16x32_bf16 v[6:9], v[164:167], v[204:207], v[58:61]
	v_mfma_f32_16x16x32_bf16 v[10:13], v[188:191], v[204:207], v[50:53]
	v_mfma_f32_16x16x32_bf16 v[2:5], v[164:167], v[14:17], v[62:65]
	v_mfma_f32_16x16x32_bf16 v[18:21], v[184:187], v[216:219], v[6:9]
	v_mfma_f32_16x16x32_bf16 v[6:9], v[188:191], v[14:17], v[54:57]
	v_mfma_f32_16x16x32_bf16 v[22:25], v[192:195], v[216:219], v[10:13]
	v_mfma_f32_16x16x32_bf16 v[10:13], v[196:199], v[14:17], v[46:49]
	v_mfma_f32_16x16x32_bf16 v[14:17], v[224:227], v[14:17], v[38:41]
	v_mfma_f32_16x16x32_bf16 v[2:5], v[184:187], v[30:33], v[2:5]
	v_mfma_f32_16x16x32_bf16 v[6:9], v[192:195], v[30:33], v[6:9]
	v_mfma_f32_16x16x32_bf16 v[10:13], v[220:223], v[30:33], v[10:13]
	v_mfma_f32_16x16x32_bf16 v[26:29], v[196:199], v[204:207], v[42:45]
	v_mfma_f32_16x16x32_bf16 v[14:17], v[232:235], v[30:33], v[14:17]
	v_mfma_f32_16x16x32_bf16 v[30:33], v[224:227], v[204:207], v[34:37]
	v_mfma_f32_16x16x32_bf16 v[26:29], v[220:223], v[216:219], v[26:29]
	v_mfma_f32_16x16x32_bf16 v[30:33], v[232:235], v[216:219], v[30:33]
	v_mfma_f32_16x16x32_bf16 v[38:41], v[164:167], v[240:243], v[152:155]
	v_mfma_f32_16x16x32_bf16 v[42:45], v[188:191], v[240:243], v[160:163]
	v_mfma_f32_16x16x32_bf16 v[46:49], v[196:199], v[240:243], v[228:231]
	v_mfma_f32_16x16x32_bf16 v[34:37], v[164:167], v[140:143], v[148:151]
	v_mfma_f32_16x16x32_bf16 v[50:53], v[184:187], v[144:147], v[38:41]
	v_mfma_f32_16x16x32_bf16 v[38:41], v[188:191], v[140:143], v[156:159]
	v_mfma_f32_16x16x32_bf16 v[54:57], v[192:195], v[144:147], v[42:45]
	v_mfma_f32_16x16x32_bf16 v[42:45], v[196:199], v[140:143], v[208:211]
	v_mfma_f32_16x16x32_bf16 v[58:61], v[220:223], v[144:147], v[46:49]
	v_mfma_f32_16x16x32_bf16 v[46:49], v[224:227], v[140:143], v[212:215]
	v_mfma_f32_16x16x32_bf16 v[62:65], v[224:227], v[240:243], v[200:203]
	v_mfma_f32_16x16x32_bf16 v[34:37], v[184:187], v[236:239], v[34:37]
	v_mfma_f32_16x16x32_bf16 v[38:41], v[192:195], v[236:239], v[38:41]
	v_mfma_f32_16x16x32_bf16 v[42:45], v[220:223], v[236:239], v[42:45]
	v_mfma_f32_16x16x32_bf16 v[46:49], v[232:235], v[236:239], v[46:49]
	v_mfma_f32_16x16x32_bf16 v[62:65], v[232:235], v[144:147], v[62:65]
	v_readlane_b32 s4, v245, 33
	v_readlane_b32 s5, v245, 34
	s_and_b64 vcc, exec, s[4:5]
	s_barrier
	s_cbranch_vccz .LBB0_101
	s_barrier

; #define LDA(dst, b, h) for (int m = 0; m < 4; ++m) for (int k = 0; k < 2; ++k) \
;     dst[m][k] = *reinterpret_cast<const bf16x8*>((char*)SA(b, h) + lds_byte(wr * 64 + m * 16 + fr, k * 32 + fq * 8))
; #define LDB(dst, b, h) for (int n = 0; n < 2; ++n) for (int k = 0; k < 2; ++k) \
;     dst[n][k] = *reinterpret_cast<const bf16x8*>((char*)SB(b, h) + lds_byte(wc * 32 + n * 16 + fr, k * 32 + fq * 8))
; #define MMA(ai, bj, At, Bt_) do { __builtin_amdgcn_s_setprio(1); \
;     for (int m = 0; m < 4; ++m) for (int n = 0; n < 2; ++n) for (int k = 0; k < 2; ++k) \
;       acc[ai][bj][m][n] = __builtin_amdgcn_mfma_f32_16x16x32_bf16(At[m][k], Bt_[n][k], acc[ai][bj][m][n], 0, 0, 0); \
;     __builtin_amdgcn_s_setprio(0); } while (0)
; #define WAIT_L(n) asm volatile("s_waitcnt lgkmcnt(" #n ")" ::: "memory")
; #define BAR __builtin_amdgcn_s_barrier()
; #define SCHED __builtin_amdgcn_sched_barrier(0)
;     ...
;       LDB(B0, 0, 0); SCHED; LDA(At, 0, 0); STAGE(SA(1, 1), A, brow + HALF, t + 1);
;       WAIT_L(8); BAR; WAIT_L(0); MMA(0, 0, At, B0); BAR; SCHED;
;       LDB(B1, 0, 1); STAGE(SB(0, 0), Bt, bcol, t + 2);
;       BAR; WAIT_L(0); MMA(0, 1, At, B1); BAR;
;       LDA(At, 0, 1); STAGE(SA(0, 0), A, brow, t + 2);
;       BAR; WAIT_L(0); MMA(1, 0, At, B0); BAR; SCHED;
.LBB0_155:
	v_add_u32_e32 v143, s2, v142
	ds_read_b128 v[146:149], v143
	ds_read_b128 v[150:153], v143 offset:1024
	ds_read_b128 v[154:157], v143 offset:2048
	ds_read_b128 v[158:161], v143 offset:3072
	s_add_u32 s40, s30, s10
	s_addc_u32 s41, s31, s11
	s_add_u32 s42, s40, 0x80080
	s_addc_u32 s43, s41, 0
	s_add_i32 s39, s24, 0xc000
	ds_read_b128 v[162:165], v133
	ds_read_b128 v[184:187], v133 offset:1024
	ds_read_b128 v[188:191], v134
	ds_read_b128 v[192:195], v134 offset:1024
	ds_read_b128 v[196:199], v137
	ds_read_b128 v[200:203], v137 offset:1024
	ds_read_b128 v[204:207], v139
	ds_read_b128 v[208:211], v139 offset:1024
	s_mov_b32 m0, s39
	v_lshl_add_u64 v[144:145], s[42:43], 0, v[0:1]
	s_add_i32 s38, s24, 0xe000
	global_load_lds_dwordx4 v[144:145], off
	v_lshl_add_u64 v[144:145], s[42:43], 0, v[140:141]
	s_mov_b32 m0, s38
	s_nop 0
	global_load_lds_dwordx4 v[144:145], off
	s_waitcnt lgkmcnt(8)
	s_barrier
	s_waitcnt lgkmcnt(0)
	s_waitcnt lgkmcnt(0)
	v_mfma_f32_16x16x32_bf16 v[126:129], v[162:165], v[146:149], v[126:129]
	v_mfma_f32_16x16x32_bf16 v[122:125], v[162:165], v[154:157], v[122:125]
	v_mfma_f32_16x16x32_bf16 v[118:121], v[188:191], v[146:149], v[118:121]
	v_mfma_f32_16x16x32_bf16 v[114:117], v[188:191], v[154:157], v[114:117]
	v_mfma_f32_16x16x32_bf16 v[110:113], v[196:199], v[146:149], v[110:113]
	v_mfma_f32_16x16x32_bf16 v[106:109], v[196:199], v[154:157], v[106:109]
	v_mfma_f32_16x16x32_bf16 v[102:105], v[204:207], v[146:149], v[102:105]
	v_mfma_f32_16x16x32_bf16 v[98:101], v[204:207], v[154:157], v[98:101]
	v_mfma_f32_16x16x32_bf16 v[126:129], v[184:187], v[150:153], v[126:129]
	v_mfma_f32_16x16x32_bf16 v[122:125], v[184:187], v[158:161], v[122:125]
	v_mfma_f32_16x16x32_bf16 v[118:121], v[192:195], v[150:153], v[118:121]
	v_mfma_f32_16x16x32_bf16 v[114:117], v[192:195], v[158:161], v[114:117]
	v_mfma_f32_16x16x32_bf16 v[110:113], v[200:203], v[150:153], v[110:113]
	v_mfma_f32_16x16x32_bf16 v[106:109], v[200:203], v[158:161], v[106:109]
	v_mfma_f32_16x16x32_bf16 v[102:105], v[208:211], v[150:153], v[102:105]
	v_mfma_f32_16x16x32_bf16 v[98:101], v[208:211], v[158:161], v[98:101]
	s_barrier
	s_add_u32 s42, s34, s10
	s_addc_u32 s43, s35, s11
	s_add_u32 s44, s42, 0x100
	v_add_u32_e32 v144, s76, v142
	s_addc_u32 s45, s43, 0
	s_mov_b32 m0, s25
	ds_read_b128 v[212:215], v144
	ds_read_b128 v[216:219], v144 offset:1024
	ds_read_b128 v[220:223], v144 offset:2048
	ds_read_b128 v[224:227], v144 offset:3072
	s_nop 0
	v_lshl_add_u64 v[166:167], s[44:45], 0, v[0:1]
	global_load_lds_dwordx4 v[166:167], off
	v_lshl_add_u64 v[166:167], s[44:45], 0, v[140:141]
	s_mov_b32 m0, s26
	s_nop 0
	global_load_lds_dwordx4 v[166:167], off
	s_barrier
	s_waitcnt lgkmcnt(0)
	s_waitcnt lgkmcnt(0)
	v_mfma_f32_16x16x32_bf16 v[94:97], v[162:165], v[212:215], v[94:97]
	v_mfma_f32_16x16x32_bf16 v[90:93], v[162:165], v[220:223], v[90:93]
	v_mfma_f32_16x16x32_bf16 v[86:89], v[188:191], v[212:215], v[86:89]
	v_mfma_f32_16x16x32_bf16 v[82:85], v[188:191], v[220:223], v[82:85]
	v_mfma_f32_16x16x32_bf16 v[78:81], v[196:199], v[212:215], v[78:81]
	v_mfma_f32_16x16x32_bf16 v[74:77], v[196:199], v[220:223], v[74:77]
	v_mfma_f32_16x16x32_bf16 v[70:73], v[204:207], v[212:215], v[70:73]
	v_mfma_f32_16x16x32_bf16 v[66:69], v[204:207], v[220:223], v[66:69]
	v_mfma_f32_16x16x32_bf16 v[94:97], v[184:187], v[216:219], v[94:97]
	v_mfma_f32_16x16x32_bf16 v[90:93], v[184:187], v[224:227], v[90:93]
	v_mfma_f32_16x16x32_bf16 v[86:89], v[192:195], v[216:219], v[86:89]
	v_mfma_f32_16x16x32_bf16 v[82:85], v[192:195], v[224:227], v[82:85]
	v_mfma_f32_16x16x32_bf16 v[78:81], v[200:203], v[216:219], v[78:81]
	v_mfma_f32_16x16x32_bf16 v[74:77], v[200:203], v[224:227], v[74:77]
	v_mfma_f32_16x16x32_bf16 v[70:73], v[208:211], v[216:219], v[70:73]
	v_mfma_f32_16x16x32_bf16 v[66:69], v[208:211], v[224:227], v[66:69]
	s_barrier
	s_add_u32 s44, s40, 0x100
	s_addc_u32 s45, s41, 0
	s_mov_b32 m0, s24
	ds_read_b128 v[162:165], v133 offset:16384
	ds_read_b128 v[184:187], v133 offset:17408
	ds_read_b128 v[188:191], v134 offset:16384
	ds_read_b128 v[192:195], v134 offset:17408
	ds_read_b128 v[196:199], v137 offset:16384
	ds_read_b128 v[200:203], v137 offset:17408
	ds_read_b128 v[204:207], v139 offset:16384
	ds_read_b128 v[208:211], v139 offset:17408
	s_nop 0
	v_lshl_add_u64 v[166:167], s[44:45], 0, v[0:1]
	global_load_lds_dwordx4 v[166:167], off
	v_lshl_add_u64 v[166:167], s[44:45], 0, v[140:141]
	s_mov_b32 m0, s9
	s_nop 0
	global_load_lds_dwordx4 v[166:167], off
	s_barrier
	s_waitcnt lgkmcnt(0)
	s_waitcnt lgkmcnt(0)
	v_mfma_f32_16x16x32_bf16 v[62:65], v[162:165], v[146:149], v[62:65]
	v_mfma_f32_16x16x32_bf16 v[58:61], v[162:165], v[154:157], v[58:61]
	v_mfma_f32_16x16x32_bf16 v[54:57], v[188:191], v[146:149], v[54:57]
	v_mfma_f32_16x16x32_bf16 v[50:53], v[188:191], v[154:157], v[50:53]
	v_mfma_f32_16x16x32_bf16 v[46:49], v[196:199], v[146:149], v[46:49]
	v_mfma_f32_16x16x32_bf16 v[42:45], v[196:199], v[154:157], v[42:45]
	v_mfma_f32_16x16x32_bf16 v[38:41], v[204:207], v[146:149], v[38:41]
	v_mfma_f32_16x16x32_bf16 v[34:37], v[204:207], v[154:157], v[34:37]
	v_mfma_f32_16x16x32_bf16 v[62:65], v[184:187], v[150:153], v[62:65]
	v_mfma_f32_16x16x32_bf16 v[58:61], v[184:187], v[158:161], v[58:61]
	v_mfma_f32_16x16x32_bf16 v[54:57], v[192:195], v[150:153], v[54:57]
	v_mfma_f32_16x16x32_bf16 v[50:53], v[192:195], v[158:161], v[50:53]
	v_mfma_f32_16x16x32_bf16 v[46:49], v[200:203], v[150:153], v[46:49]
	v_mfma_f32_16x16x32_bf16 v[42:45], v[200:203], v[158:161], v[42:45]
	v_mfma_f32_16x16x32_bf16 v[38:41], v[208:211], v[150:153], v[38:41]
	v_mfma_f32_16x16x32_bf16 v[34:37], v[208:211], v[158:161], v[34:37]
	s_barrier
; #define LDA(dst, b, h) for (int m = 0; m < 4; ++m) for (int k = 0; k < 2; ++k) \
;     dst[m][k] = *reinterpret_cast<const bf16x8*>((char*)SA(b, h) + lds_byte(wr * 64 + m * 16 + fr, k * 32 + fq * 8))
; #define LDB(dst, b, h) for (int n = 0; n < 2; ++n) for (int k = 0; k < 2; ++k) \
;     dst[n][k] = *reinterpret_cast<const bf16x8*>((char*)SB(b, h) + lds_byte(wc * 32 + n * 16 + fr, k * 32 + fq * 8))
; #define MMA(ai, bj, At, Bt_) do { __builtin_amdgcn_s_setprio(1); \
;     for (int m = 0; m < 4; ++m) for (int n = 0; n < 2; ++n) for (int k = 0; k < 2; ++k) \
;       acc[ai][bj][m][n] = __builtin_amdgcn_mfma_f32_16x16x32_bf16(At[m][k], Bt_[n][k], acc[ai][bj][m][n], 0, 0, 0); \
;     __builtin_amdgcn_s_setprio(0); } while (0)
; #define WAIT_V(n) asm volatile("s_waitcnt vmcnt(" #n ")" ::: "memory")
; #define WAIT_L(n) asm volatile("s_waitcnt lgkmcnt(" #n ")" ::: "memory")
; #define BAR __builtin_amdgcn_s_barrier()
; #define SCHED __builtin_amdgcn_sched_barrier(0)
;     ...
;       STAGE(SB(0, 1), Bt, bcol + HALF, t + 2);
;       WAIT_V(6); BAR; MMA(1, 1, At, B1); BAR;
;       LDB(B0, 1, 0); SCHED; LDA(At, 1, 0); STAGE(SA(0, 1), A, brow + HALF, t + 2);
;       WAIT_L(8); BAR; WAIT_L(0); MMA(0, 0, At, B0); BAR; SCHED;
;       LDB(B1, 1, 1); STAGE(SB(1, 0), Bt, bcol, t + 3);
;       BAR; WAIT_L(0); MMA(0, 1, At, B1); BAR;
;       LDA(At, 1, 1); STAGE(SA(1, 0), A, brow, t + 3);
	s_add_u32 s44, s42, 0x80100
	s_addc_u32 s45, s43, 0
	s_mov_b32 m0, s27
	s_nop 0
	v_lshl_add_u64 v[146:147], s[44:45], 0, v[0:1]
	global_load_lds_dwordx4 v[146:147], off
	v_lshl_add_u64 v[146:147], s[44:45], 0, v[140:141]
	s_mov_b32 m0, s28
	s_nop 0
	global_load_lds_dwordx4 v[146:147], off
	s_waitcnt vmcnt(6)
	s_barrier
	v_mfma_f32_16x16x32_bf16 v[30:33], v[162:165], v[212:215], v[30:33]
	v_mfma_f32_16x16x32_bf16 v[26:29], v[162:165], v[220:223], v[26:29]
	v_mfma_f32_16x16x32_bf16 v[22:25], v[188:191], v[212:215], v[22:25]
	v_mfma_f32_16x16x32_bf16 v[18:21], v[188:191], v[220:223], v[18:21]
	v_mfma_f32_16x16x32_bf16 v[14:17], v[196:199], v[212:215], v[14:17]
	v_mfma_f32_16x16x32_bf16 v[10:13], v[196:199], v[220:223], v[10:13]
	v_mfma_f32_16x16x32_bf16 v[6:9], v[204:207], v[212:215], v[6:9]
	v_mfma_f32_16x16x32_bf16 v[2:5], v[204:207], v[220:223], v[2:5]
	v_mfma_f32_16x16x32_bf16 v[30:33], v[184:187], v[216:219], v[30:33]
	v_mfma_f32_16x16x32_bf16 v[26:29], v[184:187], v[224:227], v[26:29]
	v_mfma_f32_16x16x32_bf16 v[22:25], v[192:195], v[216:219], v[22:25]
	v_mfma_f32_16x16x32_bf16 v[18:21], v[192:195], v[224:227], v[18:21]
	v_mfma_f32_16x16x32_bf16 v[14:17], v[200:203], v[216:219], v[14:17]
	v_mfma_f32_16x16x32_bf16 v[10:13], v[200:203], v[224:227], v[10:13]
	v_mfma_f32_16x16x32_bf16 v[6:9], v[208:211], v[216:219], v[6:9]
	v_mfma_f32_16x16x32_bf16 v[2:5], v[208:211], v[224:227], v[2:5]
	s_barrier
	v_add_u32_e32 v145, s77, v142
	ds_read_b128 v[148:151], v145
	ds_read_b128 v[152:155], v145 offset:1024
	ds_read_b128 v[156:159], v145 offset:2048
	ds_read_b128 v[160:163], v145 offset:3072
	s_add_u32 s44, s40, 0x80100
	s_addc_u32 s45, s41, 0
	s_mov_b32 m0, s7
	ds_read_b128 v[164:167], v133 offset:32768
	ds_read_b128 v[184:187], v133 offset:33792
	ds_read_b128 v[188:191], v134 offset:32768
	ds_read_b128 v[192:195], v134 offset:33792
	ds_read_b128 v[196:199], v137 offset:32768
	ds_read_b128 v[200:203], v137 offset:33792
	ds_read_b128 v[204:207], v139 offset:32768
	ds_read_b128 v[208:211], v139 offset:33792
	s_nop 0
	v_lshl_add_u64 v[146:147], s[44:45], 0, v[0:1]
	global_load_lds_dwordx4 v[146:147], off
	v_lshl_add_u64 v[146:147], s[44:45], 0, v[140:141]
	s_mov_b32 m0, s29
	s_nop 0
	global_load_lds_dwordx4 v[146:147], off
	s_waitcnt lgkmcnt(8)
	s_barrier
	s_waitcnt lgkmcnt(0)
	s_waitcnt lgkmcnt(0)
	v_mfma_f32_16x16x32_bf16 v[126:129], v[164:167], v[148:151], v[126:129]
	v_mfma_f32_16x16x32_bf16 v[122:125], v[164:167], v[156:159], v[122:125]
	v_mfma_f32_16x16x32_bf16 v[118:121], v[188:191], v[148:151], v[118:121]
	v_mfma_f32_16x16x32_bf16 v[114:117], v[188:191], v[156:159], v[114:117]
	v_mfma_f32_16x16x32_bf16 v[110:113], v[196:199], v[148:151], v[110:113]
	v_mfma_f32_16x16x32_bf16 v[106:109], v[196:199], v[156:159], v[106:109]
	v_mfma_f32_16x16x32_bf16 v[102:105], v[204:207], v[148:151], v[102:105]
	v_mfma_f32_16x16x32_bf16 v[98:101], v[204:207], v[156:159], v[98:101]
	v_mfma_f32_16x16x32_bf16 v[126:129], v[184:187], v[152:155], v[126:129]
	v_mfma_f32_16x16x32_bf16 v[122:125], v[184:187], v[160:163], v[122:125]
	v_mfma_f32_16x16x32_bf16 v[118:121], v[192:195], v[152:155], v[118:121]
	v_mfma_f32_16x16x32_bf16 v[114:117], v[192:195], v[160:163], v[114:117]
	v_mfma_f32_16x16x32_bf16 v[110:113], v[200:203], v[152:155], v[110:113]
	v_mfma_f32_16x16x32_bf16 v[106:109], v[200:203], v[160:163], v[106:109]
	v_mfma_f32_16x16x32_bf16 v[102:105], v[208:211], v[152:155], v[102:105]
	v_mfma_f32_16x16x32_bf16 v[98:101], v[208:211], v[160:163], v[98:101]
	s_barrier
	s_add_u32 s44, s42, 0x180
	v_add_u32_e32 v146, s78, v142
	s_addc_u32 s45, s43, 0
	s_mov_b32 m0, s12
	ds_read_b128 v[212:215], v146
	ds_read_b128 v[216:219], v146 offset:1024
	ds_read_b128 v[220:223], v146 offset:2048
	ds_read_b128 v[224:227], v146 offset:3072
	s_nop 0
	v_lshl_add_u64 v[228:229], s[44:45], 0, v[0:1]
	global_load_lds_dwordx4 v[228:229], off
	v_lshl_add_u64 v[228:229], s[44:45], 0, v[140:141]
	s_mov_b32 m0, s13
	s_nop 0
	global_load_lds_dwordx4 v[228:229], off
	s_barrier
	s_waitcnt lgkmcnt(0)
	s_waitcnt lgkmcnt(0)
	v_mfma_f32_16x16x32_bf16 v[94:97], v[164:167], v[212:215], v[94:97]
	v_mfma_f32_16x16x32_bf16 v[90:93], v[164:167], v[220:223], v[90:93]
	v_mfma_f32_16x16x32_bf16 v[86:89], v[188:191], v[212:215], v[86:89]
	v_mfma_f32_16x16x32_bf16 v[82:85], v[188:191], v[220:223], v[82:85]
	v_mfma_f32_16x16x32_bf16 v[78:81], v[196:199], v[212:215], v[78:81]
	v_mfma_f32_16x16x32_bf16 v[74:77], v[196:199], v[220:223], v[74:77]
	v_mfma_f32_16x16x32_bf16 v[70:73], v[204:207], v[212:215], v[70:73]
	v_mfma_f32_16x16x32_bf16 v[66:69], v[204:207], v[220:223], v[66:69]
	v_mfma_f32_16x16x32_bf16 v[94:97], v[184:187], v[216:219], v[94:97]
	v_mfma_f32_16x16x32_bf16 v[90:93], v[184:187], v[224:227], v[90:93]
	v_mfma_f32_16x16x32_bf16 v[86:89], v[192:195], v[216:219], v[86:89]
	v_mfma_f32_16x16x32_bf16 v[82:85], v[192:195], v[224:227], v[82:85]
	v_mfma_f32_16x16x32_bf16 v[78:81], v[200:203], v[216:219], v[78:81]
	v_mfma_f32_16x16x32_bf16 v[74:77], v[200:203], v[224:227], v[74:77]
	v_mfma_f32_16x16x32_bf16 v[70:73], v[208:211], v[216:219], v[70:73]
	v_mfma_f32_16x16x32_bf16 v[66:69], v[208:211], v[224:227], v[66:69]
	s_barrier
	s_add_u32 s40, s40, 0x180
	s_addc_u32 s41, s41, 0
	s_mov_b32 m0, s14
	ds_read_b128 v[164:167], v133 offset:49152
	ds_read_b128 v[184:187], v133 offset:50176
	ds_read_b128 v[188:191], v134 offset:49152
	ds_read_b128 v[192:195], v134 offset:50176
	ds_read_b128 v[196:199], v137 offset:49152
	ds_read_b128 v[200:203], v137 offset:50176
	ds_read_b128 v[204:207], v139 offset:49152
	ds_read_b128 v[208:211], v139 offset:50176
	s_nop 0
	v_lshl_add_u64 v[228:229], s[40:41], 0, v[0:1]
	global_load_lds_dwordx4 v[228:229], off
	v_lshl_add_u64 v[228:229], s[40:41], 0, v[140:141]
	s_mov_b32 m0, s15
	s_nop 0
	global_load_lds_dwordx4 v[228:229], off
	s_barrier
; #define LDA(dst, b, h) for (int m = 0; m < 4; ++m) for (int k = 0; k < 2; ++k) \
;     dst[m][k] = *reinterpret_cast<const bf16x8*>((char*)SA(b, h) + lds_byte(wr * 64 + m * 16 + fr, k * 32 + fq * 8))
; #define LDB(dst, b, h) for (int n = 0; n < 2; ++n) for (int k = 0; k < 2; ++k) \
;     dst[n][k] = *reinterpret_cast<const bf16x8*>((char*)SB(b, h) + lds_byte(wc * 32 + n * 16 + fr, k * 32 + fq * 8))
; #define MMA(ai, bj, At, Bt_) do { __builtin_amdgcn_s_setprio(1); \
;     for (int m = 0; m < 4; ++m) for (int n = 0; n < 2; ++n) for (int k = 0; k < 2; ++k) \
;       acc[ai][bj][m][n] = __builtin_amdgcn_mfma_f32_16x16x32_bf16(At[m][k], Bt_[n][k], acc[ai][bj][m][n], 0, 0, 0); \
;     __builtin_amdgcn_s_setprio(0); } while (0)
; #define WAIT_V(n) asm volatile("s_waitcnt vmcnt(" #n ")" ::: "memory")
; #define WAIT_L(n) asm volatile("s_waitcnt lgkmcnt(" #n ")" ::: "memory")
; #define BAR __builtin_amdgcn_s_barrier()
; #define SCHED __builtin_amdgcn_sched_barrier(0)
;     ...
;       BAR; WAIT_L(0); MMA(1, 0, At, B0); BAR; SCHED;
;       STAGE(SB(1, 1), Bt, bcol + HALF, t + 3);
;       WAIT_V(6); BAR; MMA(1, 1, At, B1); BAR;
;     }
;     { LDB(B0, 0, 0); LDA(At, 0, 0); STAGE(SA(1, 1), A, brow + HALF, nt - 1);
;       BAR; WAIT_L(0); MMA(0, 0, At, B0); BAR;
;       LDB(B1, 0, 1); BAR; WAIT_L(0); MMA(0, 1, At, B1); BAR;
	s_waitcnt lgkmcnt(0)
	s_waitcnt lgkmcnt(0)
	v_mfma_f32_16x16x32_bf16 v[62:65], v[164:167], v[148:151], v[62:65]
	v_mfma_f32_16x16x32_bf16 v[58:61], v[164:167], v[156:159], v[58:61]
	v_mfma_f32_16x16x32_bf16 v[54:57], v[188:191], v[148:151], v[54:57]
	v_mfma_f32_16x16x32_bf16 v[50:53], v[188:191], v[156:159], v[50:53]
	v_mfma_f32_16x16x32_bf16 v[46:49], v[196:199], v[148:151], v[46:49]
	v_mfma_f32_16x16x32_bf16 v[42:45], v[196:199], v[156:159], v[42:45]
	v_mfma_f32_16x16x32_bf16 v[38:41], v[204:207], v[148:151], v[38:41]
	v_mfma_f32_16x16x32_bf16 v[34:37], v[204:207], v[156:159], v[34:37]
	v_mfma_f32_16x16x32_bf16 v[62:65], v[184:187], v[152:155], v[62:65]
	v_mfma_f32_16x16x32_bf16 v[58:61], v[184:187], v[160:163], v[58:61]
	v_mfma_f32_16x16x32_bf16 v[54:57], v[192:195], v[152:155], v[54:57]
	v_mfma_f32_16x16x32_bf16 v[50:53], v[192:195], v[160:163], v[50:53]
	v_mfma_f32_16x16x32_bf16 v[46:49], v[200:203], v[152:155], v[46:49]
	v_mfma_f32_16x16x32_bf16 v[42:45], v[200:203], v[160:163], v[42:45]
	v_mfma_f32_16x16x32_bf16 v[38:41], v[208:211], v[152:155], v[38:41]
	v_mfma_f32_16x16x32_bf16 v[34:37], v[208:211], v[160:163], v[34:37]
	s_barrier
	s_add_u32 s40, s42, 0x80180
	s_addc_u32 s41, s43, 0
	s_mov_b32 m0, s16
	s_nop 0
	v_lshl_add_u64 v[148:149], s[40:41], 0, v[0:1]
	global_load_lds_dwordx4 v[148:149], off
	v_lshl_add_u64 v[148:149], s[40:41], 0, v[140:141]
	s_mov_b32 m0, s17
	s_nop 0
	global_load_lds_dwordx4 v[148:149], off
	s_add_i32 s37, s37, 2
	s_add_u32 s10, s10, 0x100
	s_addc_u32 s11, s11, 0
	s_cmp_gt_u32 s37, 27
	s_waitcnt vmcnt(6)
	s_barrier
	v_mfma_f32_16x16x32_bf16 v[30:33], v[164:167], v[212:215], v[30:33]
	v_mfma_f32_16x16x32_bf16 v[26:29], v[164:167], v[220:223], v[26:29]
	v_mfma_f32_16x16x32_bf16 v[22:25], v[188:191], v[212:215], v[22:25]
	v_mfma_f32_16x16x32_bf16 v[18:21], v[188:191], v[220:223], v[18:21]
	v_mfma_f32_16x16x32_bf16 v[14:17], v[196:199], v[212:215], v[14:17]
	v_mfma_f32_16x16x32_bf16 v[10:13], v[196:199], v[220:223], v[10:13]
	v_mfma_f32_16x16x32_bf16 v[6:9], v[204:207], v[212:215], v[6:9]
	v_mfma_f32_16x16x32_bf16 v[2:5], v[204:207], v[220:223], v[2:5]
	v_mfma_f32_16x16x32_bf16 v[30:33], v[184:187], v[216:219], v[30:33]
	v_mfma_f32_16x16x32_bf16 v[26:29], v[184:187], v[224:227], v[26:29]
	v_mfma_f32_16x16x32_bf16 v[22:25], v[192:195], v[216:219], v[22:25]
	v_mfma_f32_16x16x32_bf16 v[18:21], v[192:195], v[224:227], v[18:21]
	v_mfma_f32_16x16x32_bf16 v[14:17], v[200:203], v[216:219], v[14:17]
	v_mfma_f32_16x16x32_bf16 v[10:13], v[200:203], v[224:227], v[10:13]
	v_mfma_f32_16x16x32_bf16 v[6:9], v[208:211], v[216:219], v[6:9]
	v_mfma_f32_16x16x32_bf16 v[2:5], v[208:211], v[224:227], v[2:5]
	s_barrier
	s_cbranch_scc0 .LBB0_155
	s_add_u32 s4, s4, 0xf80
	s_addc_u32 s5, s5, 0
	s_mov_b32 m0, s39
	ds_read_b128 v[148:151], v143
	ds_read_b128 v[152:155], v143 offset:1024
	ds_read_b128 v[156:159], v143 offset:2048
	ds_read_b128 v[160:163], v143 offset:3072
	ds_read_b128 v[164:167], v133
	ds_read_b128 v[184:187], v133 offset:1024
	ds_read_b128 v[188:191], v134
	ds_read_b128 v[192:195], v134 offset:1024
	ds_read_b128 v[196:199], v137
	ds_read_b128 v[200:203], v137 offset:1024
	ds_read_b128 v[204:207], v139
	ds_read_b128 v[208:211], v139 offset:1024
	s_nop 0
	v_lshl_add_u64 v[142:143], s[4:5], 0, v[0:1]
	global_load_lds_dwordx4 v[142:143], off
	v_lshl_add_u64 v[140:141], s[4:5], 0, v[140:141]
	s_mov_b32 m0, s38
	s_nop 0
	global_load_lds_dwordx4 v[140:141], off
	s_barrier
	s_waitcnt lgkmcnt(0)
	s_waitcnt lgkmcnt(0)
	v_mfma_f32_16x16x32_bf16 v[126:129], v[164:167], v[148:151], v[126:129]
	v_mfma_f32_16x16x32_bf16 v[118:121], v[188:191], v[148:151], v[118:121]
	v_mfma_f32_16x16x32_bf16 v[110:113], v[196:199], v[148:151], v[110:113]
	v_mfma_f32_16x16x32_bf16 v[102:105], v[204:207], v[148:151], v[102:105]
	v_mfma_f32_16x16x32_bf16 v[126:129], v[184:187], v[152:155], v[126:129]
	v_mfma_f32_16x16x32_bf16 v[122:125], v[164:167], v[156:159], v[122:125]
	v_mfma_f32_16x16x32_bf16 v[118:121], v[192:195], v[152:155], v[118:121]
	v_mfma_f32_16x16x32_bf16 v[114:117], v[188:191], v[156:159], v[114:117]
	v_mfma_f32_16x16x32_bf16 v[110:113], v[200:203], v[152:155], v[110:113]
	v_mfma_f32_16x16x32_bf16 v[106:109], v[196:199], v[156:159], v[106:109]
	v_mfma_f32_16x16x32_bf16 v[102:105], v[208:211], v[152:155], v[102:105]
	v_mfma_f32_16x16x32_bf16 v[98:101], v[204:207], v[156:159], v[98:101]
	v_mfma_f32_16x16x32_bf16 v[140:143], v[184:187], v[160:163], v[122:125]
	v_mfma_f32_16x16x32_bf16 v[212:215], v[192:195], v[160:163], v[114:117]
	v_mfma_f32_16x16x32_bf16 v[216:219], v[200:203], v[160:163], v[106:109]
	v_mfma_f32_16x16x32_bf16 v[220:223], v[208:211], v[160:163], v[98:101]
	s_barrier
	s_nop 1
	ds_read_b128 v[98:101], v144
	ds_read_b128 v[106:109], v144 offset:1024
	ds_read_b128 v[114:117], v144 offset:2048
	ds_read_b128 v[122:125], v144 offset:3072
	s_barrier
	s_waitcnt lgkmcnt(0)
	s_waitcnt lgkmcnt(0)
	v_mfma_f32_16x16x32_bf16 v[94:97], v[164:167], v[98:101], v[94:97]
	v_mfma_f32_16x16x32_bf16 v[86:89], v[188:191], v[98:101], v[86:89]
	v_mfma_f32_16x16x32_bf16 v[78:81], v[196:199], v[98:101], v[78:81]
	v_mfma_f32_16x16x32_bf16 v[70:73], v[204:207], v[98:101], v[70:73]
	v_mfma_f32_16x16x32_bf16 v[94:97], v[184:187], v[106:109], v[94:97]
	v_mfma_f32_16x16x32_bf16 v[90:93], v[164:167], v[114:117], v[90:93]
	v_mfma_f32_16x16x32_bf16 v[86:89], v[192:195], v[106:109], v[86:89]
	v_mfma_f32_16x16x32_bf16 v[82:85], v[188:191], v[114:117], v[82:85]
	v_mfma_f32_16x16x32_bf16 v[78:81], v[200:203], v[106:109], v[78:81]
	v_mfma_f32_16x16x32_bf16 v[74:77], v[196:199], v[114:117], v[74:77]
	v_mfma_f32_16x16x32_bf16 v[70:73], v[208:211], v[106:109], v[70:73]
	v_mfma_f32_16x16x32_bf16 v[66:69], v[204:207], v[114:117], v[66:69]
	v_mfma_f32_16x16x32_bf16 v[164:167], v[184:187], v[122:125], v[90:93]
	v_mfma_f32_16x16x32_bf16 v[184:187], v[192:195], v[122:125], v[82:85]
	v_mfma_f32_16x16x32_bf16 v[188:191], v[200:203], v[122:125], v[74:77]
	v_mfma_f32_16x16x32_bf16 v[192:195], v[208:211], v[122:125], v[66:69]
	s_barrier
; #define LDA(dst, b, h) for (int m = 0; m < 4; ++m) for (int k = 0; k < 2; ++k) \
;     dst[m][k] = *reinterpret_cast<const bf16x8*>((char*)SA(b, h) + lds_byte(wr * 64 + m * 16 + fr, k * 32 + fq * 8))
; #define LDB(dst, b, h) for (int n = 0; n < 2; ++n) for (int k = 0; k < 2; ++k) \
;     dst[n][k] = *reinterpret_cast<const bf16x8*>((char*)SB(b, h) + lds_byte(wc * 32 + n * 16 + fr, k * 32 + fq * 8))
; #define MMA(ai, bj, At, Bt_) do { __builtin_amdgcn_s_setprio(1); \
;     for (int m = 0; m < 4; ++m) for (int n = 0; n < 2; ++n) for (int k = 0; k < 2; ++k) \
;       acc[ai][bj][m][n] = __builtin_amdgcn_mfma_f32_16x16x32_bf16(At[m][k], Bt_[n][k], acc[ai][bj][m][n], 0, 0, 0); \
;     __builtin_amdgcn_s_setprio(0); } while (0)
; #define WAIT_V(n) asm volatile("s_waitcnt vmcnt(" #n ")" ::: "memory")
; #define WAIT_L(n) asm volatile("s_waitcnt lgkmcnt(" #n ")" ::: "memory")
; #define BAR __builtin_amdgcn_s_barrier()
;     ...
;       LDA(At, 0, 1); WAIT_V(4); BAR; WAIT_L(0); MMA(1, 0, At, B0); MMA(1, 1, At, B1); BAR; }
;     { LDB(B0, 1, 0); LDA(At, 1, 0); WAIT_V(2); BAR; WAIT_L(0); MMA(0, 0, At, B0); BAR;
	s_nop 1
	ds_read_b128 v[66:69], v133 offset:16384
	ds_read_b128 v[74:77], v133 offset:17408
	ds_read_b128 v[82:85], v134 offset:16384
	ds_read_b128 v[90:93], v134 offset:17408
	ds_read_b128 v[196:199], v137 offset:16384
	ds_read_b128 v[200:203], v137 offset:17408
	ds_read_b128 v[204:207], v139 offset:16384
	ds_read_b128 v[208:211], v139 offset:17408
	s_waitcnt vmcnt(4)
	s_barrier
	s_waitcnt lgkmcnt(0)
	s_waitcnt lgkmcnt(0)
	v_mfma_f32_16x16x32_bf16 v[62:65], v[66:69], v[148:151], v[62:65]
	v_mfma_f32_16x16x32_bf16 v[54:57], v[82:85], v[148:151], v[54:57]
	v_mfma_f32_16x16x32_bf16 v[46:49], v[196:199], v[148:151], v[46:49]
	v_mfma_f32_16x16x32_bf16 v[38:41], v[204:207], v[148:151], v[38:41]
	v_mfma_f32_16x16x32_bf16 v[62:65], v[74:77], v[152:155], v[62:65]
	v_mfma_f32_16x16x32_bf16 v[58:61], v[66:69], v[156:159], v[58:61]
	v_mfma_f32_16x16x32_bf16 v[54:57], v[90:93], v[152:155], v[54:57]
	v_mfma_f32_16x16x32_bf16 v[50:53], v[82:85], v[156:159], v[50:53]
	v_mfma_f32_16x16x32_bf16 v[46:49], v[200:203], v[152:155], v[46:49]
	v_mfma_f32_16x16x32_bf16 v[42:45], v[196:199], v[156:159], v[42:45]
	v_mfma_f32_16x16x32_bf16 v[38:41], v[208:211], v[152:155], v[38:41]
	v_mfma_f32_16x16x32_bf16 v[34:37], v[204:207], v[156:159], v[34:37]
	v_mfma_f32_16x16x32_bf16 v[224:227], v[74:77], v[160:163], v[58:61]
	v_mfma_f32_16x16x32_bf16 v[228:231], v[90:93], v[160:163], v[50:53]
	v_mfma_f32_16x16x32_bf16 v[232:235], v[200:203], v[160:163], v[42:45]
	v_mfma_f32_16x16x32_bf16 v[148:151], v[208:211], v[160:163], v[34:37]
	v_mfma_f32_16x16x32_bf16 v[30:33], v[66:69], v[98:101], v[30:33]
	v_mfma_f32_16x16x32_bf16 v[22:25], v[82:85], v[98:101], v[22:25]
	v_mfma_f32_16x16x32_bf16 v[14:17], v[196:199], v[98:101], v[14:17]
	v_mfma_f32_16x16x32_bf16 v[6:9], v[204:207], v[98:101], v[6:9]
	v_mfma_f32_16x16x32_bf16 v[30:33], v[74:77], v[106:109], v[30:33]
	v_mfma_f32_16x16x32_bf16 v[26:29], v[66:69], v[114:117], v[26:29]
	v_mfma_f32_16x16x32_bf16 v[22:25], v[90:93], v[106:109], v[22:25]
	v_mfma_f32_16x16x32_bf16 v[18:21], v[82:85], v[114:117], v[18:21]
	v_mfma_f32_16x16x32_bf16 v[14:17], v[200:203], v[106:109], v[14:17]
	v_mfma_f32_16x16x32_bf16 v[10:13], v[196:199], v[114:117], v[10:13]
	v_mfma_f32_16x16x32_bf16 v[6:9], v[208:211], v[106:109], v[6:9]
	v_mfma_f32_16x16x32_bf16 v[2:5], v[204:207], v[114:117], v[2:5]
	v_mfma_f32_16x16x32_bf16 v[152:155], v[74:77], v[122:125], v[26:29]
	v_mfma_f32_16x16x32_bf16 v[156:159], v[90:93], v[122:125], v[18:21]
	v_mfma_f32_16x16x32_bf16 v[160:163], v[200:203], v[122:125], v[10:13]
	v_mfma_f32_16x16x32_bf16 v[196:199], v[208:211], v[122:125], v[2:5]
	s_barrier
	s_nop 1
	ds_read_b128 v[2:5], v145
	ds_read_b128 v[10:13], v145 offset:1024
	ds_read_b128 v[200:203], v145 offset:2048
	ds_read_b128 v[204:207], v145 offset:3072
	ds_read_b128 v[18:21], v133 offset:32768
	ds_read_b128 v[26:29], v133 offset:33792
	ds_read_b128 v[34:37], v134 offset:32768
	ds_read_b128 v[42:45], v134 offset:33792
	ds_read_b128 v[50:53], v137 offset:32768
	ds_read_b128 v[58:61], v137 offset:33792
	ds_read_b128 v[208:211], v139 offset:32768
	ds_read_b128 v[236:239], v139 offset:33792
	s_waitcnt vmcnt(2)
	s_barrier
	s_waitcnt lgkmcnt(0)
	s_waitcnt lgkmcnt(0)
	v_mfma_f32_16x16x32_bf16 v[66:69], v[18:21], v[2:5], v[126:129]
	v_mfma_f32_16x16x32_bf16 v[122:125], v[26:29], v[10:13], v[66:69]
	v_mfma_f32_16x16x32_bf16 v[66:69], v[18:21], v[200:203], v[140:143]
	v_mfma_f32_16x16x32_bf16 v[114:117], v[26:29], v[204:207], v[66:69]
	v_mfma_f32_16x16x32_bf16 v[66:69], v[34:37], v[2:5], v[118:121]
	v_mfma_f32_16x16x32_bf16 v[106:109], v[42:45], v[10:13], v[66:69]
	v_mfma_f32_16x16x32_bf16 v[66:69], v[34:37], v[200:203], v[212:215]
	v_mfma_f32_16x16x32_bf16 v[98:101], v[42:45], v[204:207], v[66:69]
	v_mfma_f32_16x16x32_bf16 v[66:69], v[50:53], v[2:5], v[110:113]
	v_mfma_f32_16x16x32_bf16 v[90:93], v[58:61], v[10:13], v[66:69]
	v_mfma_f32_16x16x32_bf16 v[66:69], v[50:53], v[200:203], v[216:219]
	v_mfma_f32_16x16x32_bf16 v[82:85], v[58:61], v[204:207], v[66:69]
	v_mfma_f32_16x16x32_bf16 v[66:69], v[208:211], v[2:5], v[102:105]
	v_mfma_f32_16x16x32_bf16 v[74:77], v[236:239], v[10:13], v[66:69]
	v_mfma_f32_16x16x32_bf16 v[66:69], v[208:211], v[200:203], v[220:223]
	v_mfma_f32_16x16x32_bf16 v[66:69], v[236:239], v[204:207], v[66:69]
	s_barrier
; #define LDA(dst, b, h) for (int m = 0; m < 4; ++m) for (int k = 0; k < 2; ++k) \
;     dst[m][k] = *reinterpret_cast<const bf16x8*>((char*)SA(b, h) + lds_byte(wr * 64 + m * 16 + fr, k * 32 + fq * 8))
; #define LDB(dst, b, h) for (int n = 0; n < 2; ++n) for (int k = 0; k < 2; ++k) \
;     dst[n][k] = *reinterpret_cast<const bf16x8*>((char*)SB(b, h) + lds_byte(wc * 32 + n * 16 + fr, k * 32 + fq * 8))
; #define MMA(ai, bj, At, Bt_) do { __builtin_amdgcn_s_setprio(1); \
;     for (int m = 0; m < 4; ++m) for (int n = 0; n < 2; ++n) for (int k = 0; k < 2; ++k) \
;       acc[ai][bj][m][n] = __builtin_amdgcn_mfma_f32_16x16x32_bf16(At[m][k], Bt_[n][k], acc[ai][bj][m][n], 0, 0, 0); \
;     __builtin_amdgcn_s_setprio(0); } while (0)
; #define WAIT_V(n) asm volatile("s_waitcnt vmcnt(" #n ")" ::: "memory")
; #define WAIT_L(n) asm volatile("s_waitcnt lgkmcnt(" #n ")" ::: "memory")
; #define BAR __builtin_amdgcn_s_barrier()
;     ...
;     { LDB(B0, 1, 0); LDA(At, 1, 0); WAIT_V(2); BAR; WAIT_L(0); MMA(0, 0, At, B0); BAR;
;       LDB(B1, 1, 1); WAIT_V(0); BAR; WAIT_L(0); MMA(0, 1, At, B1); BAR;
;       LDA(At, 1, 1); BAR; WAIT_L(0); MMA(1, 0, At, B0); MMA(1, 1, At, B1); BAR; }
;     if (wr == 0) BAR;
	ds_read_b128 v[140:143], v146
	ds_read_b128 v[212:215], v146 offset:1024
	ds_read_b128 v[216:219], v146 offset:2048
	ds_read_b128 v[144:147], v146 offset:3072
	s_waitcnt vmcnt(0)
	s_barrier
	s_waitcnt lgkmcnt(0)
	s_waitcnt lgkmcnt(0)
	v_mfma_f32_16x16x32_bf16 v[94:97], v[18:21], v[140:143], v[94:97]
	v_mfma_f32_16x16x32_bf16 v[18:21], v[18:21], v[216:219], v[164:167]
	v_mfma_f32_16x16x32_bf16 v[118:121], v[26:29], v[144:147], v[18:21]
	v_mfma_f32_16x16x32_bf16 v[18:21], v[34:37], v[140:143], v[86:89]
	v_mfma_f32_16x16x32_bf16 v[110:113], v[42:45], v[212:215], v[18:21]
	v_mfma_f32_16x16x32_bf16 v[18:21], v[34:37], v[216:219], v[184:187]
	v_mfma_f32_16x16x32_bf16 v[102:105], v[42:45], v[144:147], v[18:21]
	v_mfma_f32_16x16x32_bf16 v[18:21], v[50:53], v[140:143], v[78:81]
	v_mfma_f32_16x16x32_bf16 v[126:129], v[26:29], v[212:215], v[94:97]
	v_mfma_f32_16x16x32_bf16 v[94:97], v[58:61], v[212:215], v[18:21]
	v_mfma_f32_16x16x32_bf16 v[18:21], v[50:53], v[216:219], v[188:191]
	v_mfma_f32_16x16x32_bf16 v[86:89], v[58:61], v[144:147], v[18:21]
	v_mfma_f32_16x16x32_bf16 v[18:21], v[208:211], v[140:143], v[70:73]
	v_mfma_f32_16x16x32_bf16 v[78:81], v[236:239], v[212:215], v[18:21]
	v_mfma_f32_16x16x32_bf16 v[18:21], v[208:211], v[216:219], v[192:195]
	v_mfma_f32_16x16x32_bf16 v[70:73], v[236:239], v[144:147], v[18:21]
	s_barrier
	ds_read_b128 v[164:167], v133 offset:49152
	ds_read_b128 v[184:187], v133 offset:50176
	ds_read_b128 v[188:191], v134 offset:49152
	ds_read_b128 v[192:195], v134 offset:50176
	ds_read_b128 v[208:211], v137 offset:49152
	ds_read_b128 v[220:223], v137 offset:50176
	ds_read_b128 v[236:239], v139 offset:49152
	ds_read_b128 v[240:243], v139 offset:50176
	s_barrier
	s_waitcnt lgkmcnt(0)
	s_waitcnt lgkmcnt(0)
	v_mfma_f32_16x16x32_bf16 v[18:21], v[164:167], v[2:5], v[62:65]
	v_mfma_f32_16x16x32_bf16 v[58:61], v[184:187], v[10:13], v[18:21]
	v_mfma_f32_16x16x32_bf16 v[18:21], v[164:167], v[200:203], v[224:227]
	v_mfma_f32_16x16x32_bf16 v[50:53], v[184:187], v[204:207], v[18:21]
	v_mfma_f32_16x16x32_bf16 v[18:21], v[188:191], v[2:5], v[54:57]
	v_mfma_f32_16x16x32_bf16 v[42:45], v[192:195], v[10:13], v[18:21]
	v_mfma_f32_16x16x32_bf16 v[18:21], v[188:191], v[200:203], v[228:231]
	v_mfma_f32_16x16x32_bf16 v[34:37], v[192:195], v[204:207], v[18:21]
	v_mfma_f32_16x16x32_bf16 v[18:21], v[208:211], v[2:5], v[46:49]
	v_mfma_f32_16x16x32_bf16 v[2:5], v[236:239], v[2:5], v[38:41]
	v_mfma_f32_16x16x32_bf16 v[26:29], v[220:223], v[10:13], v[18:21]
	v_mfma_f32_16x16x32_bf16 v[18:21], v[208:211], v[200:203], v[232:235]
	v_mfma_f32_16x16x32_bf16 v[10:13], v[240:243], v[10:13], v[2:5]
	v_mfma_f32_16x16x32_bf16 v[2:5], v[236:239], v[200:203], v[148:151]
	v_mfma_f32_16x16x32_bf16 v[18:21], v[220:223], v[204:207], v[18:21]
	v_mfma_f32_16x16x32_bf16 v[2:5], v[240:243], v[204:207], v[2:5]
	v_mfma_f32_16x16x32_bf16 v[30:33], v[164:167], v[140:143], v[30:33]
	v_mfma_f32_16x16x32_bf16 v[62:65], v[184:187], v[212:215], v[30:33]
	v_mfma_f32_16x16x32_bf16 v[30:33], v[164:167], v[216:219], v[152:155]
	v_mfma_f32_16x16x32_bf16 v[22:25], v[188:191], v[140:143], v[22:25]
	v_mfma_f32_16x16x32_bf16 v[14:17], v[208:211], v[140:143], v[14:17]
	v_mfma_f32_16x16x32_bf16 v[54:57], v[184:187], v[144:147], v[30:33]
	v_mfma_f32_16x16x32_bf16 v[46:49], v[192:195], v[212:215], v[22:25]
	v_mfma_f32_16x16x32_bf16 v[22:25], v[188:191], v[216:219], v[156:159]
	v_mfma_f32_16x16x32_bf16 v[30:33], v[220:223], v[212:215], v[14:17]
	v_mfma_f32_16x16x32_bf16 v[14:17], v[208:211], v[216:219], v[160:163]
	v_mfma_f32_16x16x32_bf16 v[6:9], v[236:239], v[140:143], v[6:9]
	v_mfma_f32_16x16x32_bf16 v[38:41], v[192:195], v[144:147], v[22:25]
	v_mfma_f32_16x16x32_bf16 v[22:25], v[220:223], v[144:147], v[14:17]
	v_mfma_f32_16x16x32_bf16 v[14:17], v[240:243], v[212:215], v[6:9]
	v_mfma_f32_16x16x32_bf16 v[6:9], v[236:239], v[216:219], v[196:199]
	v_mfma_f32_16x16x32_bf16 v[6:9], v[240:243], v[144:147], v[6:9]
	v_readlane_b32 s4, v245, 33
	v_readlane_b32 s5, v245, 34
	s_and_b64 vcc, exec, s[4:5]
	s_barrier
	s_cbranch_vccz .LBB0_158
	s_barrier

; #define LDA(dst, b, h) for (int m = 0; m < 4; ++m) for (int k = 0; k < 2; ++k) \
;     dst[m][k] = *reinterpret_cast<const bf16x8*>((char*)SA(b, h) + lds_byte(wr * 64 + m * 16 + fr, k * 32 + fq * 8))
; #define LDB(dst, b, h) for (int n = 0; n < 2; ++n) for (int k = 0; k < 2; ++k) \
;     dst[n][k] = *reinterpret_cast<const bf16x8*>((char*)SB(b, h) + lds_byte(wc * 32 + n * 16 + fr, k * 32 + fq * 8))
; #define MMA(ai, bj, At, Bt_) do { __builtin_amdgcn_s_setprio(1); \
;     for (int m = 0; m < 4; ++m) for (int n = 0; n < 2; ++n) for (int k = 0; k < 2; ++k) \
;       acc[ai][bj][m][n] = __builtin_amdgcn_mfma_f32_16x16x32_bf16(At[m][k], Bt_[n][k], acc[ai][bj][m][n], 0, 0, 0); \
;     __builtin_amdgcn_s_setprio(0); } while (0)
; #define WAIT_L(n) asm volatile("s_waitcnt lgkmcnt(" #n ")" ::: "memory")
; #define BAR __builtin_amdgcn_s_barrier()
; #define SCHED __builtin_amdgcn_sched_barrier(0)
;     ...
;       LDB(B0, 0, 0); SCHED; LDA(At, 0, 0); STAGE(SA(1, 1), A, brow + HALF, t + 1);
;       WAIT_L(8); BAR; WAIT_L(0); MMA(0, 0, At, B0); BAR; SCHED;
;       LDB(B1, 0, 1); STAGE(SB(0, 0), Bt, bcol, t + 2);
;       BAR; WAIT_L(0); MMA(0, 1, At, B1); BAR;
;       LDA(At, 0, 1); STAGE(SA(0, 0), A, brow, t + 2);
;       BAR; WAIT_L(0); MMA(1, 0, At, B0); BAR; SCHED;
.LBB0_202:
	v_add_u32_e32 v143, s2, v142
	ds_read_b128 v[146:149], v143
	ds_read_b128 v[150:153], v143 offset:1024
	ds_read_b128 v[154:157], v143 offset:2048
	ds_read_b128 v[158:161], v143 offset:3072
	s_add_u32 s66, s50, s16
	s_addc_u32 s67, s51, s17
	s_add_i32 s58, s21, 0xc000
	ds_read_b128 v[162:165], v133
	ds_read_b128 v[184:187], v133 offset:1024
	ds_read_b128 v[188:191], v134
	ds_read_b128 v[192:195], v134 offset:1024
	ds_read_b128 v[196:199], v137
	ds_read_b128 v[200:203], v137 offset:1024
	ds_read_b128 v[204:207], v139
	ds_read_b128 v[208:211], v139 offset:1024
	s_mov_b32 m0, s58
	v_lshl_add_u64 v[144:145], s[66:67], 0, v[0:1]
	s_add_i32 s57, s21, 0xe000
	global_load_lds_dwordx4 v[144:145], off
	v_lshl_add_u64 v[144:145], s[66:67], 0, v[140:141]
	s_mov_b32 m0, s57
	s_nop 0
	global_load_lds_dwordx4 v[144:145], off
	s_waitcnt lgkmcnt(8)
	s_barrier
	s_waitcnt lgkmcnt(0)
	s_waitcnt lgkmcnt(0)
	v_mfma_f32_16x16x32_bf16 v[126:129], v[162:165], v[146:149], v[126:129]
	v_mfma_f32_16x16x32_bf16 v[122:125], v[162:165], v[154:157], v[122:125]
	v_mfma_f32_16x16x32_bf16 v[118:121], v[188:191], v[146:149], v[118:121]
	v_mfma_f32_16x16x32_bf16 v[114:117], v[188:191], v[154:157], v[114:117]
	v_mfma_f32_16x16x32_bf16 v[110:113], v[196:199], v[146:149], v[110:113]
	v_mfma_f32_16x16x32_bf16 v[106:109], v[196:199], v[154:157], v[106:109]
	v_mfma_f32_16x16x32_bf16 v[102:105], v[204:207], v[146:149], v[102:105]
	v_mfma_f32_16x16x32_bf16 v[98:101], v[204:207], v[154:157], v[98:101]
	v_mfma_f32_16x16x32_bf16 v[126:129], v[184:187], v[150:153], v[126:129]
	v_mfma_f32_16x16x32_bf16 v[122:125], v[184:187], v[158:161], v[122:125]
	v_mfma_f32_16x16x32_bf16 v[118:121], v[192:195], v[150:153], v[118:121]
	v_mfma_f32_16x16x32_bf16 v[114:117], v[192:195], v[158:161], v[114:117]
	v_mfma_f32_16x16x32_bf16 v[110:113], v[200:203], v[150:153], v[110:113]
	v_mfma_f32_16x16x32_bf16 v[106:109], v[200:203], v[158:161], v[106:109]
	v_mfma_f32_16x16x32_bf16 v[102:105], v[208:211], v[150:153], v[102:105]
	v_mfma_f32_16x16x32_bf16 v[98:101], v[208:211], v[158:161], v[98:101]
	s_barrier
	s_add_i32 s55, s55, 2
	s_add_u32 s59, s11, s16
	s_addc_u32 s63, s44, s17
	s_add_u32 s66, s59, 0x100
	v_add_u32_e32 v144, s76, v142
	s_addc_u32 s67, s63, 0
	s_mov_b32 m0, s29
	ds_read_b128 v[212:215], v144
	ds_read_b128 v[216:219], v144 offset:1024
	ds_read_b128 v[220:223], v144 offset:2048
	ds_read_b128 v[224:227], v144 offset:3072
	s_nop 0
	v_lshl_add_u64 v[166:167], s[66:67], 0, v[0:1]
	global_load_lds_dwordx4 v[166:167], off
	v_lshl_add_u64 v[166:167], s[66:67], 0, v[140:141]
	s_mov_b32 m0, s30
	s_nop 0
	global_load_lds_dwordx4 v[166:167], off
	s_barrier
	s_waitcnt lgkmcnt(0)
	s_waitcnt lgkmcnt(0)
	v_mfma_f32_16x16x32_bf16 v[94:97], v[162:165], v[212:215], v[94:97]
	v_mfma_f32_16x16x32_bf16 v[90:93], v[162:165], v[220:223], v[90:93]
	v_mfma_f32_16x16x32_bf16 v[86:89], v[188:191], v[212:215], v[86:89]
	v_mfma_f32_16x16x32_bf16 v[82:85], v[188:191], v[220:223], v[82:85]
	v_mfma_f32_16x16x32_bf16 v[78:81], v[196:199], v[212:215], v[78:81]
	v_mfma_f32_16x16x32_bf16 v[74:77], v[196:199], v[220:223], v[74:77]
	v_mfma_f32_16x16x32_bf16 v[70:73], v[204:207], v[212:215], v[70:73]
	v_mfma_f32_16x16x32_bf16 v[66:69], v[204:207], v[220:223], v[66:69]
	v_mfma_f32_16x16x32_bf16 v[94:97], v[184:187], v[216:219], v[94:97]
	v_mfma_f32_16x16x32_bf16 v[90:93], v[184:187], v[224:227], v[90:93]
	v_mfma_f32_16x16x32_bf16 v[86:89], v[192:195], v[216:219], v[86:89]
	v_mfma_f32_16x16x32_bf16 v[82:85], v[192:195], v[224:227], v[82:85]
	v_mfma_f32_16x16x32_bf16 v[78:81], v[200:203], v[216:219], v[78:81]
	v_mfma_f32_16x16x32_bf16 v[74:77], v[200:203], v[224:227], v[74:77]
	v_mfma_f32_16x16x32_bf16 v[70:73], v[208:211], v[216:219], v[70:73]
	v_mfma_f32_16x16x32_bf16 v[66:69], v[208:211], v[224:227], v[66:69]
	s_barrier
	s_add_u32 s65, s13, s16
	s_addc_u32 s70, s45, s17
	s_add_u32 s66, s65, 0x100
	s_addc_u32 s67, s70, 0
	s_mov_b32 m0, s21
	ds_read_b128 v[162:165], v133 offset:16384
	ds_read_b128 v[184:187], v133 offset:17408
	ds_read_b128 v[188:191], v134 offset:16384
	ds_read_b128 v[192:195], v134 offset:17408
	ds_read_b128 v[196:199], v137 offset:16384
	ds_read_b128 v[200:203], v137 offset:17408
	ds_read_b128 v[204:207], v139 offset:16384
	ds_read_b128 v[208:211], v139 offset:17408
	s_nop 0
	v_lshl_add_u64 v[166:167], s[66:67], 0, v[0:1]
	global_load_lds_dwordx4 v[166:167], off
	v_lshl_add_u64 v[166:167], s[66:67], 0, v[140:141]
	s_mov_b32 m0, s31
	s_nop 0
	global_load_lds_dwordx4 v[166:167], off
	s_barrier
	s_waitcnt lgkmcnt(0)
	s_waitcnt lgkmcnt(0)
	v_mfma_f32_16x16x32_bf16 v[62:65], v[162:165], v[146:149], v[62:65]
	v_mfma_f32_16x16x32_bf16 v[58:61], v[162:165], v[154:157], v[58:61]
	v_mfma_f32_16x16x32_bf16 v[54:57], v[188:191], v[146:149], v[54:57]
	v_mfma_f32_16x16x32_bf16 v[50:53], v[188:191], v[154:157], v[50:53]
	v_mfma_f32_16x16x32_bf16 v[46:49], v[196:199], v[146:149], v[46:49]
	v_mfma_f32_16x16x32_bf16 v[42:45], v[196:199], v[154:157], v[42:45]
	v_mfma_f32_16x16x32_bf16 v[38:41], v[204:207], v[146:149], v[38:41]
	v_mfma_f32_16x16x32_bf16 v[34:37], v[204:207], v[154:157], v[34:37]
	v_mfma_f32_16x16x32_bf16 v[62:65], v[184:187], v[150:153], v[62:65]
	v_mfma_f32_16x16x32_bf16 v[58:61], v[184:187], v[158:161], v[58:61]
	v_mfma_f32_16x16x32_bf16 v[54:57], v[192:195], v[150:153], v[54:57]
	v_mfma_f32_16x16x32_bf16 v[50:53], v[192:195], v[158:161], v[50:53]
	v_mfma_f32_16x16x32_bf16 v[46:49], v[200:203], v[150:153], v[46:49]
	v_mfma_f32_16x16x32_bf16 v[42:45], v[200:203], v[158:161], v[42:45]
	v_mfma_f32_16x16x32_bf16 v[38:41], v[208:211], v[150:153], v[38:41]
	v_mfma_f32_16x16x32_bf16 v[34:37], v[208:211], v[158:161], v[34:37]
	s_barrier
; #define LDA(dst, b, h) for (int m = 0; m < 4; ++m) for (int k = 0; k < 2; ++k) \
;     dst[m][k] = *reinterpret_cast<const bf16x8*>((char*)SA(b, h) + lds_byte(wr * 64 + m * 16 + fr, k * 32 + fq * 8))
; #define LDB(dst, b, h) for (int n = 0; n < 2; ++n) for (int k = 0; k < 2; ++k) \
;     dst[n][k] = *reinterpret_cast<const bf16x8*>((char*)SB(b, h) + lds_byte(wc * 32 + n * 16 + fr, k * 32 + fq * 8))
; #define MMA(ai, bj, At, Bt_) do { __builtin_amdgcn_s_setprio(1); \
;     for (int m = 0; m < 4; ++m) for (int n = 0; n < 2; ++n) for (int k = 0; k < 2; ++k) \
;       acc[ai][bj][m][n] = __builtin_amdgcn_mfma_f32_16x16x32_bf16(At[m][k], Bt_[n][k], acc[ai][bj][m][n], 0, 0, 0); \
;     __builtin_amdgcn_s_setprio(0); } while (0)
; #define WAIT_V(n) asm volatile("s_waitcnt vmcnt(" #n ")" ::: "memory")
; #define WAIT_L(n) asm volatile("s_waitcnt lgkmcnt(" #n ")" ::: "memory")
; #define BAR __builtin_amdgcn_s_barrier()
; #define SCHED __builtin_amdgcn_sched_barrier(0)
;     ...
;       STAGE(SB(0, 1), Bt, bcol + HALF, t + 2);
;       WAIT_V(6); BAR; MMA(1, 1, At, B1); BAR;
;       LDB(B0, 1, 0); SCHED; LDA(At, 1, 0); STAGE(SA(0, 1), A, brow + HALF, t + 2);
;       WAIT_L(8); BAR; WAIT_L(0); MMA(0, 0, At, B0); BAR; SCHED;
;       LDB(B1, 1, 1); STAGE(SB(1, 0), Bt, bcol, t + 3);
;       BAR; WAIT_L(0); MMA(0, 1, At, B1); BAR;
;       LDA(At, 1, 1); STAGE(SA(1, 0), A, brow, t + 3);
	s_add_u32 s66, s59, 0x80100
	s_addc_u32 s67, s63, 0
	s_mov_b32 m0, s34
	s_nop 0
	v_lshl_add_u64 v[146:147], s[66:67], 0, v[0:1]
	global_load_lds_dwordx4 v[146:147], off
	v_lshl_add_u64 v[146:147], s[66:67], 0, v[140:141]
	s_mov_b32 m0, s35
	s_nop 0
	global_load_lds_dwordx4 v[146:147], off
	s_waitcnt vmcnt(6)
	s_barrier
	v_mfma_f32_16x16x32_bf16 v[30:33], v[162:165], v[212:215], v[30:33]
	v_mfma_f32_16x16x32_bf16 v[26:29], v[162:165], v[220:223], v[26:29]
	v_mfma_f32_16x16x32_bf16 v[22:25], v[188:191], v[212:215], v[22:25]
	v_mfma_f32_16x16x32_bf16 v[18:21], v[188:191], v[220:223], v[18:21]
	v_mfma_f32_16x16x32_bf16 v[14:17], v[196:199], v[212:215], v[14:17]
	v_mfma_f32_16x16x32_bf16 v[10:13], v[196:199], v[220:223], v[10:13]
	v_mfma_f32_16x16x32_bf16 v[6:9], v[204:207], v[212:215], v[6:9]
	v_mfma_f32_16x16x32_bf16 v[2:5], v[204:207], v[220:223], v[2:5]
	v_mfma_f32_16x16x32_bf16 v[30:33], v[184:187], v[216:219], v[30:33]
	v_mfma_f32_16x16x32_bf16 v[26:29], v[184:187], v[224:227], v[26:29]
	v_mfma_f32_16x16x32_bf16 v[22:25], v[192:195], v[216:219], v[22:25]
	v_mfma_f32_16x16x32_bf16 v[18:21], v[192:195], v[224:227], v[18:21]
	v_mfma_f32_16x16x32_bf16 v[14:17], v[200:203], v[216:219], v[14:17]
	v_mfma_f32_16x16x32_bf16 v[10:13], v[200:203], v[224:227], v[10:13]
	v_mfma_f32_16x16x32_bf16 v[6:9], v[208:211], v[216:219], v[6:9]
	v_mfma_f32_16x16x32_bf16 v[2:5], v[208:211], v[224:227], v[2:5]
	s_barrier
	v_add_u32_e32 v145, s77, v142
	ds_read_b128 v[148:151], v145
	ds_read_b128 v[152:155], v145 offset:1024
	ds_read_b128 v[156:159], v145 offset:2048
	ds_read_b128 v[160:163], v145 offset:3072
	s_add_u32 s66, s65, 0x80100
	s_addc_u32 s67, s70, 0
	s_mov_b32 m0, s37
	ds_read_b128 v[164:167], v133 offset:32768
	ds_read_b128 v[184:187], v133 offset:33792
	ds_read_b128 v[188:191], v134 offset:32768
	ds_read_b128 v[192:195], v134 offset:33792
	ds_read_b128 v[196:199], v137 offset:32768
	ds_read_b128 v[200:203], v137 offset:33792
	ds_read_b128 v[204:207], v139 offset:32768
	ds_read_b128 v[208:211], v139 offset:33792
	s_nop 0
	v_lshl_add_u64 v[146:147], s[66:67], 0, v[0:1]
	global_load_lds_dwordx4 v[146:147], off
	v_lshl_add_u64 v[146:147], s[66:67], 0, v[140:141]
	s_mov_b32 m0, s38
	s_nop 0
	global_load_lds_dwordx4 v[146:147], off
	s_waitcnt lgkmcnt(8)
	s_barrier
	s_waitcnt lgkmcnt(0)
	s_waitcnt lgkmcnt(0)
	v_mfma_f32_16x16x32_bf16 v[126:129], v[164:167], v[148:151], v[126:129]
	v_mfma_f32_16x16x32_bf16 v[122:125], v[164:167], v[156:159], v[122:125]
	v_mfma_f32_16x16x32_bf16 v[118:121], v[188:191], v[148:151], v[118:121]
	v_mfma_f32_16x16x32_bf16 v[114:117], v[188:191], v[156:159], v[114:117]
	v_mfma_f32_16x16x32_bf16 v[110:113], v[196:199], v[148:151], v[110:113]
	v_mfma_f32_16x16x32_bf16 v[106:109], v[196:199], v[156:159], v[106:109]
	v_mfma_f32_16x16x32_bf16 v[102:105], v[204:207], v[148:151], v[102:105]
	v_mfma_f32_16x16x32_bf16 v[98:101], v[204:207], v[156:159], v[98:101]
	v_mfma_f32_16x16x32_bf16 v[126:129], v[184:187], v[152:155], v[126:129]
	v_mfma_f32_16x16x32_bf16 v[122:125], v[184:187], v[160:163], v[122:125]
	v_mfma_f32_16x16x32_bf16 v[118:121], v[192:195], v[152:155], v[118:121]
	v_mfma_f32_16x16x32_bf16 v[114:117], v[192:195], v[160:163], v[114:117]
	v_mfma_f32_16x16x32_bf16 v[110:113], v[200:203], v[152:155], v[110:113]
	v_mfma_f32_16x16x32_bf16 v[106:109], v[200:203], v[160:163], v[106:109]
	v_mfma_f32_16x16x32_bf16 v[102:105], v[208:211], v[152:155], v[102:105]
	v_mfma_f32_16x16x32_bf16 v[98:101], v[208:211], v[160:163], v[98:101]
	s_barrier
	s_add_u32 s66, s59, 0x180
	v_add_u32_e32 v146, s78, v142
	s_addc_u32 s67, s63, 0
	s_mov_b32 m0, s39
	ds_read_b128 v[212:215], v146
	ds_read_b128 v[216:219], v146 offset:1024
	ds_read_b128 v[220:223], v146 offset:2048
	ds_read_b128 v[224:227], v146 offset:3072
	s_nop 0
	v_lshl_add_u64 v[228:229], s[66:67], 0, v[0:1]
	global_load_lds_dwordx4 v[228:229], off
	v_lshl_add_u64 v[228:229], s[66:67], 0, v[140:141]
	s_mov_b32 m0, s40
	s_nop 0
	global_load_lds_dwordx4 v[228:229], off
	s_barrier
	s_waitcnt lgkmcnt(0)
	s_waitcnt lgkmcnt(0)
	v_mfma_f32_16x16x32_bf16 v[94:97], v[164:167], v[212:215], v[94:97]
	v_mfma_f32_16x16x32_bf16 v[90:93], v[164:167], v[220:223], v[90:93]
	v_mfma_f32_16x16x32_bf16 v[86:89], v[188:191], v[212:215], v[86:89]
	v_mfma_f32_16x16x32_bf16 v[82:85], v[188:191], v[220:223], v[82:85]
	v_mfma_f32_16x16x32_bf16 v[78:81], v[196:199], v[212:215], v[78:81]
	v_mfma_f32_16x16x32_bf16 v[74:77], v[196:199], v[220:223], v[74:77]
	v_mfma_f32_16x16x32_bf16 v[70:73], v[204:207], v[212:215], v[70:73]
	v_mfma_f32_16x16x32_bf16 v[66:69], v[204:207], v[220:223], v[66:69]
	v_mfma_f32_16x16x32_bf16 v[94:97], v[184:187], v[216:219], v[94:97]
	v_mfma_f32_16x16x32_bf16 v[90:93], v[184:187], v[224:227], v[90:93]
	v_mfma_f32_16x16x32_bf16 v[86:89], v[192:195], v[216:219], v[86:89]
	v_mfma_f32_16x16x32_bf16 v[82:85], v[192:195], v[224:227], v[82:85]
	v_mfma_f32_16x16x32_bf16 v[78:81], v[200:203], v[216:219], v[78:81]
	v_mfma_f32_16x16x32_bf16 v[74:77], v[200:203], v[224:227], v[74:77]
	v_mfma_f32_16x16x32_bf16 v[70:73], v[208:211], v[216:219], v[70:73]
	v_mfma_f32_16x16x32_bf16 v[66:69], v[208:211], v[224:227], v[66:69]
	s_barrier
	s_add_u32 s66, s65, 0x180
	s_addc_u32 s67, s70, 0
	s_mov_b32 m0, s41
	ds_read_b128 v[164:167], v133 offset:49152
	ds_read_b128 v[184:187], v133 offset:50176
	ds_read_b128 v[188:191], v134 offset:49152
	ds_read_b128 v[192:195], v134 offset:50176
	ds_read_b128 v[196:199], v137 offset:49152
	ds_read_b128 v[200:203], v137 offset:50176
	ds_read_b128 v[204:207], v139 offset:49152
	ds_read_b128 v[208:211], v139 offset:50176
	s_nop 0
	v_lshl_add_u64 v[228:229], s[66:67], 0, v[0:1]
	global_load_lds_dwordx4 v[228:229], off
	v_lshl_add_u64 v[228:229], s[66:67], 0, v[140:141]
	s_mov_b32 m0, s42
	s_nop 0
	global_load_lds_dwordx4 v[228:229], off
	s_barrier
; #define LDA(dst, b, h) for (int m = 0; m < 4; ++m) for (int k = 0; k < 2; ++k) \
;     dst[m][k] = *reinterpret_cast<const bf16x8*>((char*)SA(b, h) + lds_byte(wr * 64 + m * 16 + fr, k * 32 + fq * 8))
; #define LDB(dst, b, h) for (int n = 0; n < 2; ++n) for (int k = 0; k < 2; ++k) \
;     dst[n][k] = *reinterpret_cast<const bf16x8*>((char*)SB(b, h) + lds_byte(wc * 32 + n * 16 + fr, k * 32 + fq * 8))
; #define MMA(ai, bj, At, Bt_) do { __builtin_amdgcn_s_setprio(1); \
;     for (int m = 0; m < 4; ++m) for (int n = 0; n < 2; ++n) for (int k = 0; k < 2; ++k) \
;       acc[ai][bj][m][n] = __builtin_amdgcn_mfma_f32_16x16x32_bf16(At[m][k], Bt_[n][k], acc[ai][bj][m][n], 0, 0, 0); \
;     __builtin_amdgcn_s_setprio(0); } while (0)
; #define WAIT_V(n) asm volatile("s_waitcnt vmcnt(" #n ")" ::: "memory")
; #define WAIT_L(n) asm volatile("s_waitcnt lgkmcnt(" #n ")" ::: "memory")
; #define BAR __builtin_amdgcn_s_barrier()
; #define SCHED __builtin_amdgcn_sched_barrier(0)
;     ...
;       BAR; WAIT_L(0); MMA(1, 0, At, B0); BAR; SCHED;
;       STAGE(SB(1, 1), Bt, bcol + HALF, t + 3);
;       WAIT_V(6); BAR; MMA(1, 1, At, B1); BAR;
;     }
;     { LDB(B0, 0, 0); LDA(At, 0, 0); STAGE(SA(1, 1), A, brow + HALF, nt - 1);
;       BAR; WAIT_L(0); MMA(0, 0, At, B0); BAR;
;       LDB(B1, 0, 1); BAR; WAIT_L(0); MMA(0, 1, At, B1); BAR;
	s_waitcnt lgkmcnt(0)
	s_waitcnt lgkmcnt(0)
	v_mfma_f32_16x16x32_bf16 v[62:65], v[164:167], v[148:151], v[62:65]
	v_mfma_f32_16x16x32_bf16 v[58:61], v[164:167], v[156:159], v[58:61]
	v_mfma_f32_16x16x32_bf16 v[54:57], v[188:191], v[148:151], v[54:57]
	v_mfma_f32_16x16x32_bf16 v[50:53], v[188:191], v[156:159], v[50:53]
	v_mfma_f32_16x16x32_bf16 v[46:49], v[196:199], v[148:151], v[46:49]
	v_mfma_f32_16x16x32_bf16 v[42:45], v[196:199], v[156:159], v[42:45]
	v_mfma_f32_16x16x32_bf16 v[38:41], v[204:207], v[148:151], v[38:41]
	v_mfma_f32_16x16x32_bf16 v[34:37], v[204:207], v[156:159], v[34:37]
	v_mfma_f32_16x16x32_bf16 v[62:65], v[184:187], v[152:155], v[62:65]
	v_mfma_f32_16x16x32_bf16 v[58:61], v[184:187], v[160:163], v[58:61]
	v_mfma_f32_16x16x32_bf16 v[54:57], v[192:195], v[152:155], v[54:57]
	v_mfma_f32_16x16x32_bf16 v[50:53], v[192:195], v[160:163], v[50:53]
	v_mfma_f32_16x16x32_bf16 v[46:49], v[200:203], v[152:155], v[46:49]
	v_mfma_f32_16x16x32_bf16 v[42:45], v[200:203], v[160:163], v[42:45]
	v_mfma_f32_16x16x32_bf16 v[38:41], v[208:211], v[152:155], v[38:41]
	v_mfma_f32_16x16x32_bf16 v[34:37], v[208:211], v[160:163], v[34:37]
	s_barrier
	s_add_u32 s66, s59, 0x80180
	s_addc_u32 s67, s63, 0
	s_mov_b32 m0, s18
	s_nop 0
	v_lshl_add_u64 v[148:149], s[66:67], 0, v[0:1]
	global_load_lds_dwordx4 v[148:149], off
	v_lshl_add_u64 v[148:149], s[66:67], 0, v[140:141]
	s_mov_b32 m0, s19
	s_nop 0
	global_load_lds_dwordx4 v[148:149], off
	s_add_u32 s11, s11, 0x100
	s_addc_u32 s44, s44, 0
	s_add_u32 s13, s13, 0x100
	s_addc_u32 s45, s45, 0
	s_add_u32 s50, s50, 0x100
	s_addc_u32 s51, s51, 0
	s_cmp_ge_u32 s55, s43
	s_waitcnt vmcnt(6)
	s_barrier
	v_mfma_f32_16x16x32_bf16 v[30:33], v[164:167], v[212:215], v[30:33]
	v_mfma_f32_16x16x32_bf16 v[26:29], v[164:167], v[220:223], v[26:29]
	v_mfma_f32_16x16x32_bf16 v[22:25], v[188:191], v[212:215], v[22:25]
	v_mfma_f32_16x16x32_bf16 v[18:21], v[188:191], v[220:223], v[18:21]
	v_mfma_f32_16x16x32_bf16 v[14:17], v[196:199], v[212:215], v[14:17]
	v_mfma_f32_16x16x32_bf16 v[10:13], v[196:199], v[220:223], v[10:13]
	v_mfma_f32_16x16x32_bf16 v[6:9], v[204:207], v[212:215], v[6:9]
	v_mfma_f32_16x16x32_bf16 v[2:5], v[204:207], v[220:223], v[2:5]
	v_mfma_f32_16x16x32_bf16 v[30:33], v[184:187], v[216:219], v[30:33]
	v_mfma_f32_16x16x32_bf16 v[26:29], v[184:187], v[224:227], v[26:29]
	v_mfma_f32_16x16x32_bf16 v[22:25], v[192:195], v[216:219], v[22:25]
	v_mfma_f32_16x16x32_bf16 v[18:21], v[192:195], v[224:227], v[18:21]
	v_mfma_f32_16x16x32_bf16 v[14:17], v[200:203], v[216:219], v[14:17]
	v_mfma_f32_16x16x32_bf16 v[10:13], v[200:203], v[224:227], v[10:13]
	v_mfma_f32_16x16x32_bf16 v[6:9], v[208:211], v[216:219], v[6:9]
	v_mfma_f32_16x16x32_bf16 v[2:5], v[208:211], v[224:227], v[2:5]
	s_barrier
	s_cbranch_scc0 .LBB0_202
	s_add_i32 s11, s48, s20
	s_add_i32 s48, s11, -1
	s_lshl_b64 s[16:17], s[48:49], 7
	s_add_u32 s11, s74, s16
	s_addc_u32 s13, s75, s17
	s_add_u32 s4, s11, s4
	s_addc_u32 s5, s13, s5
	s_mov_b32 m0, s58
	ds_read_b128 v[148:151], v143
	ds_read_b128 v[152:155], v143 offset:1024
	ds_read_b128 v[156:159], v143 offset:2048
	ds_read_b128 v[160:163], v143 offset:3072
	ds_read_b128 v[164:167], v133
	ds_read_b128 v[184:187], v133 offset:1024
	ds_read_b128 v[188:191], v134
	ds_read_b128 v[192:195], v134 offset:1024
	ds_read_b128 v[196:199], v137
	ds_read_b128 v[200:203], v137 offset:1024
	ds_read_b128 v[204:207], v139
	ds_read_b128 v[208:211], v139 offset:1024
	s_nop 0
	v_lshl_add_u64 v[142:143], s[4:5], 0, v[0:1]
	global_load_lds_dwordx4 v[142:143], off
	v_lshl_add_u64 v[140:141], s[4:5], 0, v[140:141]
	s_mov_b32 m0, s57
	s_nop 0
	global_load_lds_dwordx4 v[140:141], off
	s_barrier
	s_waitcnt lgkmcnt(0)
	s_waitcnt lgkmcnt(0)
	v_mfma_f32_16x16x32_bf16 v[126:129], v[164:167], v[148:151], v[126:129]
	v_mfma_f32_16x16x32_bf16 v[122:125], v[164:167], v[156:159], v[122:125]
	v_mfma_f32_16x16x32_bf16 v[118:121], v[188:191], v[148:151], v[118:121]
	v_mfma_f32_16x16x32_bf16 v[110:113], v[196:199], v[148:151], v[110:113]
	v_mfma_f32_16x16x32_bf16 v[106:109], v[196:199], v[156:159], v[106:109]
	v_mfma_f32_16x16x32_bf16 v[102:105], v[204:207], v[148:151], v[102:105]
	v_mfma_f32_16x16x32_bf16 v[98:101], v[204:207], v[156:159], v[98:101]
	v_mfma_f32_16x16x32_bf16 v[126:129], v[184:187], v[152:155], v[126:129]
	v_mfma_f32_16x16x32_bf16 v[122:125], v[184:187], v[160:163], v[122:125]
	v_mfma_f32_16x16x32_bf16 v[118:121], v[192:195], v[152:155], v[118:121]
	v_mfma_f32_16x16x32_bf16 v[114:117], v[188:191], v[156:159], v[114:117]
	v_mfma_f32_16x16x32_bf16 v[110:113], v[200:203], v[152:155], v[110:113]
	v_mfma_f32_16x16x32_bf16 v[106:109], v[200:203], v[160:163], v[106:109]
	v_mfma_f32_16x16x32_bf16 v[102:105], v[208:211], v[152:155], v[102:105]
	v_mfma_f32_16x16x32_bf16 v[98:101], v[208:211], v[160:163], v[98:101]
	v_mfma_f32_16x16x32_bf16 v[140:143], v[192:195], v[160:163], v[114:117]
	s_barrier
	s_nop 0
	ds_read_b128 v[114:117], v144
	ds_read_b128 v[212:215], v144 offset:1024
	ds_read_b128 v[216:219], v144 offset:2048
	ds_read_b128 v[220:223], v144 offset:3072
	s_barrier
; #define LDA(dst, b, h) for (int m = 0; m < 4; ++m) for (int k = 0; k < 2; ++k) \
;     dst[m][k] = *reinterpret_cast<const bf16x8*>((char*)SA(b, h) + lds_byte(wr * 64 + m * 16 + fr, k * 32 + fq * 8))
; #define LDB(dst, b, h) for (int n = 0; n < 2; ++n) for (int k = 0; k < 2; ++k) \
;     dst[n][k] = *reinterpret_cast<const bf16x8*>((char*)SB(b, h) + lds_byte(wc * 32 + n * 16 + fr, k * 32 + fq * 8))
; #define MMA(ai, bj, At, Bt_) do { __builtin_amdgcn_s_setprio(1); \
;     for (int m = 0; m < 4; ++m) for (int n = 0; n < 2; ++n) for (int k = 0; k < 2; ++k) \
;       acc[ai][bj][m][n] = __builtin_amdgcn_mfma_f32_16x16x32_bf16(At[m][k], Bt_[n][k], acc[ai][bj][m][n], 0, 0, 0); \
;     __builtin_amdgcn_s_setprio(0); } while (0)
; #define WAIT_V(n) asm volatile("s_waitcnt vmcnt(" #n ")" ::: "memory")
; #define WAIT_L(n) asm volatile("s_waitcnt lgkmcnt(" #n ")" ::: "memory")
; #define BAR __builtin_amdgcn_s_barrier()
;     ...
;       LDB(B1, 0, 1); BAR; WAIT_L(0); MMA(0, 1, At, B1); BAR;
;       LDA(At, 0, 1); WAIT_V(4); BAR; WAIT_L(0); MMA(1, 0, At, B0); MMA(1, 1, At, B1); BAR; }
;     { LDB(B0, 1, 0); LDA(At, 1, 0); WAIT_V(2); BAR; WAIT_L(0); MMA(0, 0, At, B0); BAR;
	s_waitcnt lgkmcnt(0)
	s_waitcnt lgkmcnt(0)
	v_mfma_f32_16x16x32_bf16 v[90:93], v[164:167], v[216:219], v[90:93]
	v_mfma_f32_16x16x32_bf16 v[86:89], v[188:191], v[114:117], v[86:89]
	v_mfma_f32_16x16x32_bf16 v[94:97], v[164:167], v[114:117], v[94:97]
	v_mfma_f32_16x16x32_bf16 v[90:93], v[184:187], v[220:223], v[90:93]
	v_mfma_f32_16x16x32_bf16 v[86:89], v[192:195], v[212:215], v[86:89]
	v_mfma_f32_16x16x32_bf16 v[82:85], v[188:191], v[216:219], v[82:85]
	v_mfma_f32_16x16x32_bf16 v[78:81], v[196:199], v[114:117], v[78:81]
	v_mfma_f32_16x16x32_bf16 v[74:77], v[196:199], v[216:219], v[74:77]
	v_mfma_f32_16x16x32_bf16 v[70:73], v[204:207], v[114:117], v[70:73]
	v_mfma_f32_16x16x32_bf16 v[66:69], v[204:207], v[216:219], v[66:69]
	v_mfma_f32_16x16x32_bf16 v[224:227], v[184:187], v[212:215], v[94:97]
	v_mfma_f32_16x16x32_bf16 v[164:167], v[192:195], v[220:223], v[82:85]
	v_mfma_f32_16x16x32_bf16 v[184:187], v[200:203], v[212:215], v[78:81]
	v_mfma_f32_16x16x32_bf16 v[188:191], v[200:203], v[220:223], v[74:77]
	v_mfma_f32_16x16x32_bf16 v[192:195], v[208:211], v[212:215], v[70:73]
	v_mfma_f32_16x16x32_bf16 v[196:199], v[208:211], v[220:223], v[66:69]
	s_barrier
	s_nop 0
	ds_read_b128 v[66:69], v133 offset:16384
	ds_read_b128 v[70:73], v133 offset:17408
	ds_read_b128 v[74:77], v134 offset:16384
	ds_read_b128 v[78:81], v134 offset:17408
	ds_read_b128 v[82:85], v137 offset:16384
	ds_read_b128 v[94:97], v137 offset:17408
	ds_read_b128 v[200:203], v139 offset:16384
	ds_read_b128 v[204:207], v139 offset:17408
	s_waitcnt vmcnt(4)
	s_barrier
	s_waitcnt lgkmcnt(0)
	s_waitcnt lgkmcnt(0)
	v_mfma_f32_16x16x32_bf16 v[62:65], v[66:69], v[148:151], v[62:65]
	v_mfma_f32_16x16x32_bf16 v[58:61], v[66:69], v[156:159], v[58:61]
	v_mfma_f32_16x16x32_bf16 v[54:57], v[74:77], v[148:151], v[54:57]
	v_mfma_f32_16x16x32_bf16 v[50:53], v[74:77], v[156:159], v[50:53]
	v_mfma_f32_16x16x32_bf16 v[46:49], v[82:85], v[148:151], v[46:49]
	v_mfma_f32_16x16x32_bf16 v[42:45], v[82:85], v[156:159], v[42:45]
	v_mfma_f32_16x16x32_bf16 v[38:41], v[200:203], v[148:151], v[38:41]
	v_mfma_f32_16x16x32_bf16 v[34:37], v[200:203], v[156:159], v[34:37]
	v_mfma_f32_16x16x32_bf16 v[62:65], v[70:73], v[152:155], v[62:65]
	v_mfma_f32_16x16x32_bf16 v[58:61], v[70:73], v[160:163], v[58:61]
	v_mfma_f32_16x16x32_bf16 v[54:57], v[78:81], v[152:155], v[54:57]
	v_mfma_f32_16x16x32_bf16 v[50:53], v[78:81], v[160:163], v[50:53]
	v_mfma_f32_16x16x32_bf16 v[46:49], v[94:97], v[152:155], v[46:49]
	v_mfma_f32_16x16x32_bf16 v[42:45], v[94:97], v[160:163], v[42:45]
	v_mfma_f32_16x16x32_bf16 v[38:41], v[204:207], v[152:155], v[38:41]
	v_mfma_f32_16x16x32_bf16 v[34:37], v[204:207], v[160:163], v[34:37]
	v_mfma_f32_16x16x32_bf16 v[30:33], v[66:69], v[114:117], v[30:33]
	v_mfma_f32_16x16x32_bf16 v[26:29], v[66:69], v[216:219], v[26:29]
	v_mfma_f32_16x16x32_bf16 v[22:25], v[74:77], v[114:117], v[22:25]
	v_mfma_f32_16x16x32_bf16 v[18:21], v[74:77], v[216:219], v[18:21]
	v_mfma_f32_16x16x32_bf16 v[14:17], v[82:85], v[114:117], v[14:17]
	v_mfma_f32_16x16x32_bf16 v[10:13], v[82:85], v[216:219], v[10:13]
	v_mfma_f32_16x16x32_bf16 v[6:9], v[200:203], v[114:117], v[6:9]
	v_mfma_f32_16x16x32_bf16 v[2:5], v[200:203], v[216:219], v[2:5]
	v_mfma_f32_16x16x32_bf16 v[148:151], v[70:73], v[212:215], v[30:33]
	v_mfma_f32_16x16x32_bf16 v[152:155], v[70:73], v[220:223], v[26:29]
	v_mfma_f32_16x16x32_bf16 v[156:159], v[78:81], v[212:215], v[22:25]
	v_mfma_f32_16x16x32_bf16 v[160:163], v[78:81], v[220:223], v[18:21]
	v_mfma_f32_16x16x32_bf16 v[208:211], v[94:97], v[212:215], v[14:17]
	v_mfma_f32_16x16x32_bf16 v[228:231], v[94:97], v[220:223], v[10:13]
	v_mfma_f32_16x16x32_bf16 v[212:215], v[204:207], v[212:215], v[6:9]
	v_mfma_f32_16x16x32_bf16 v[200:203], v[204:207], v[220:223], v[2:5]
	s_barrier
	ds_read_b128 v[14:17], v145
	ds_read_b128 v[30:33], v145 offset:1024
	ds_read_b128 v[204:207], v145 offset:2048
	ds_read_b128 v[216:219], v145 offset:3072
	ds_read_b128 v[2:5], v133 offset:32768
	ds_read_b128 v[6:9], v133 offset:33792
	ds_read_b128 v[10:13], v134 offset:32768
	ds_read_b128 v[18:21], v134 offset:33792
	ds_read_b128 v[22:25], v137 offset:32768
	ds_read_b128 v[26:29], v137 offset:33792
	ds_read_b128 v[220:223], v139 offset:32768
	ds_read_b128 v[232:235], v139 offset:33792
	s_waitcnt vmcnt(2)
	s_barrier
; #define LDA(dst, b, h) for (int m = 0; m < 4; ++m) for (int k = 0; k < 2; ++k) \
;     dst[m][k] = *reinterpret_cast<const bf16x8*>((char*)SA(b, h) + lds_byte(wr * 64 + m * 16 + fr, k * 32 + fq * 8))
; #define LDB(dst, b, h) for (int n = 0; n < 2; ++n) for (int k = 0; k < 2; ++k) \
;     dst[n][k] = *reinterpret_cast<const bf16x8*>((char*)SB(b, h) + lds_byte(wc * 32 + n * 16 + fr, k * 32 + fq * 8))
; #define MMA(ai, bj, At, Bt_) do { __builtin_amdgcn_s_setprio(1); \
;     for (int m = 0; m < 4; ++m) for (int n = 0; n < 2; ++n) for (int k = 0; k < 2; ++k) \
;       acc[ai][bj][m][n] = __builtin_amdgcn_mfma_f32_16x16x32_bf16(At[m][k], Bt_[n][k], acc[ai][bj][m][n], 0, 0, 0); \
;     __builtin_amdgcn_s_setprio(0); } while (0)
; #define WAIT_V(n) asm volatile("s_waitcnt vmcnt(" #n ")" ::: "memory")
; #define WAIT_L(n) asm volatile("s_waitcnt lgkmcnt(" #n ")" ::: "memory")
; #define BAR __builtin_amdgcn_s_barrier()
;     ...
;     { LDB(B0, 1, 0); LDA(At, 1, 0); WAIT_V(2); BAR; WAIT_L(0); MMA(0, 0, At, B0); BAR;
;       LDB(B1, 1, 1); WAIT_V(0); BAR; WAIT_L(0); MMA(0, 1, At, B1); BAR;
;       LDA(At, 1, 1); BAR; WAIT_L(0); MMA(1, 0, At, B0); MMA(1, 1, At, B1); BAR; }
;     if (wr == 0) BAR;
	s_waitcnt lgkmcnt(0)
	s_waitcnt lgkmcnt(0)
	v_mfma_f32_16x16x32_bf16 v[66:69], v[2:5], v[14:17], v[126:129]
	v_mfma_f32_16x16x32_bf16 v[114:117], v[6:9], v[30:33], v[66:69]
	v_mfma_f32_16x16x32_bf16 v[66:69], v[2:5], v[204:207], v[122:125]
	v_mfma_f32_16x16x32_bf16 v[126:129], v[6:9], v[216:219], v[66:69]
	v_mfma_f32_16x16x32_bf16 v[66:69], v[10:13], v[14:17], v[118:121]
	v_mfma_f32_16x16x32_bf16 v[82:85], v[18:21], v[30:33], v[66:69]
	v_mfma_f32_16x16x32_bf16 v[66:69], v[10:13], v[204:207], v[140:143]
	v_mfma_f32_16x16x32_bf16 v[94:97], v[18:21], v[216:219], v[66:69]
	v_mfma_f32_16x16x32_bf16 v[66:69], v[22:25], v[14:17], v[110:113]
	v_mfma_f32_16x16x32_bf16 v[74:77], v[26:29], v[30:33], v[66:69]
	v_mfma_f32_16x16x32_bf16 v[66:69], v[22:25], v[204:207], v[106:109]
	v_mfma_f32_16x16x32_bf16 v[78:81], v[26:29], v[216:219], v[66:69]
	v_mfma_f32_16x16x32_bf16 v[66:69], v[220:223], v[14:17], v[102:105]
	v_mfma_f32_16x16x32_bf16 v[70:73], v[220:223], v[204:207], v[98:101]
	v_mfma_f32_16x16x32_bf16 v[66:69], v[232:235], v[30:33], v[66:69]
	v_mfma_f32_16x16x32_bf16 v[70:73], v[232:235], v[216:219], v[70:73]
	s_barrier
	ds_read_b128 v[140:143], v146
	ds_read_b128 v[236:239], v146 offset:1024
	ds_read_b128 v[240:243], v146 offset:2048
	ds_read_b128 v[144:147], v146 offset:3072
	s_waitcnt vmcnt(0)
	s_barrier
	s_waitcnt lgkmcnt(0)
	s_waitcnt lgkmcnt(0)
	v_mfma_f32_16x16x32_bf16 v[98:101], v[2:5], v[140:143], v[224:227]
	v_mfma_f32_16x16x32_bf16 v[2:5], v[2:5], v[240:243], v[90:93]
	v_mfma_f32_16x16x32_bf16 v[118:121], v[6:9], v[144:147], v[2:5]
	v_mfma_f32_16x16x32_bf16 v[2:5], v[10:13], v[140:143], v[86:89]
	v_mfma_f32_16x16x32_bf16 v[102:105], v[18:21], v[236:239], v[2:5]
	v_mfma_f32_16x16x32_bf16 v[2:5], v[10:13], v[240:243], v[164:167]
	v_mfma_f32_16x16x32_bf16 v[122:125], v[18:21], v[144:147], v[2:5]
	v_mfma_f32_16x16x32_bf16 v[2:5], v[22:25], v[140:143], v[184:187]
	v_mfma_f32_16x16x32_bf16 v[90:93], v[26:29], v[236:239], v[2:5]
	v_mfma_f32_16x16x32_bf16 v[2:5], v[22:25], v[240:243], v[188:191]
	v_mfma_f32_16x16x32_bf16 v[110:113], v[26:29], v[144:147], v[2:5]
	v_mfma_f32_16x16x32_bf16 v[2:5], v[220:223], v[140:143], v[192:195]
	v_mfma_f32_16x16x32_bf16 v[86:89], v[232:235], v[236:239], v[2:5]
	v_mfma_f32_16x16x32_bf16 v[2:5], v[220:223], v[240:243], v[196:199]
	v_mfma_f32_16x16x32_bf16 v[98:101], v[6:9], v[236:239], v[98:101]
	v_mfma_f32_16x16x32_bf16 v[106:109], v[232:235], v[144:147], v[2:5]
	s_barrier
	ds_read_b128 v[164:167], v133 offset:49152
	ds_read_b128 v[184:187], v133 offset:50176
	ds_read_b128 v[188:191], v134 offset:49152
	ds_read_b128 v[192:195], v134 offset:50176
	ds_read_b128 v[196:199], v137 offset:49152
	ds_read_b128 v[220:223], v137 offset:50176
	ds_read_b128 v[224:227], v139 offset:49152
	ds_read_b128 v[232:235], v139 offset:50176
	s_barrier
	s_waitcnt lgkmcnt(0)
	s_waitcnt lgkmcnt(0)
	v_mfma_f32_16x16x32_bf16 v[6:9], v[164:167], v[204:207], v[58:61]
	v_mfma_f32_16x16x32_bf16 v[10:13], v[188:191], v[204:207], v[50:53]
	v_mfma_f32_16x16x32_bf16 v[2:5], v[164:167], v[14:17], v[62:65]
	v_mfma_f32_16x16x32_bf16 v[18:21], v[184:187], v[216:219], v[6:9]
	v_mfma_f32_16x16x32_bf16 v[6:9], v[188:191], v[14:17], v[54:57]
	v_mfma_f32_16x16x32_bf16 v[22:25], v[192:195], v[216:219], v[10:13]
	v_mfma_f32_16x16x32_bf16 v[10:13], v[196:199], v[14:17], v[46:49]
	v_mfma_f32_16x16x32_bf16 v[14:17], v[224:227], v[14:17], v[38:41]
	v_mfma_f32_16x16x32_bf16 v[2:5], v[184:187], v[30:33], v[2:5]
	v_mfma_f32_16x16x32_bf16 v[6:9], v[192:195], v[30:33], v[6:9]
	v_mfma_f32_16x16x32_bf16 v[10:13], v[220:223], v[30:33], v[10:13]
	v_mfma_f32_16x16x32_bf16 v[26:29], v[196:199], v[204:207], v[42:45]
	v_mfma_f32_16x16x32_bf16 v[14:17], v[232:235], v[30:33], v[14:17]
	v_mfma_f32_16x16x32_bf16 v[30:33], v[224:227], v[204:207], v[34:37]
	v_mfma_f32_16x16x32_bf16 v[26:29], v[220:223], v[216:219], v[26:29]
	v_mfma_f32_16x16x32_bf16 v[30:33], v[232:235], v[216:219], v[30:33]
	v_mfma_f32_16x16x32_bf16 v[38:41], v[164:167], v[240:243], v[152:155]
	v_mfma_f32_16x16x32_bf16 v[42:45], v[188:191], v[240:243], v[160:163]
	v_mfma_f32_16x16x32_bf16 v[46:49], v[196:199], v[240:243], v[228:231]
	v_mfma_f32_16x16x32_bf16 v[34:37], v[164:167], v[140:143], v[148:151]
	v_mfma_f32_16x16x32_bf16 v[50:53], v[184:187], v[144:147], v[38:41]
	v_mfma_f32_16x16x32_bf16 v[38:41], v[188:191], v[140:143], v[156:159]
	v_mfma_f32_16x16x32_bf16 v[54:57], v[192:195], v[144:147], v[42:45]
	v_mfma_f32_16x16x32_bf16 v[42:45], v[196:199], v[140:143], v[208:211]
	v_mfma_f32_16x16x32_bf16 v[58:61], v[220:223], v[144:147], v[46:49]
	v_mfma_f32_16x16x32_bf16 v[46:49], v[224:227], v[140:143], v[212:215]
	v_mfma_f32_16x16x32_bf16 v[62:65], v[224:227], v[240:243], v[200:203]
	v_mfma_f32_16x16x32_bf16 v[34:37], v[184:187], v[236:239], v[34:37]
	v_mfma_f32_16x16x32_bf16 v[38:41], v[192:195], v[236:239], v[38:41]
	v_mfma_f32_16x16x32_bf16 v[42:45], v[220:223], v[236:239], v[42:45]
	v_mfma_f32_16x16x32_bf16 v[46:49], v[232:235], v[236:239], v[46:49]
	v_mfma_f32_16x16x32_bf16 v[62:65], v[232:235], v[144:147], v[62:65]
	v_readlane_b32 s4, v245, 33
	v_readlane_b32 s5, v245, 34
	s_and_b64 vcc, exec, s[4:5]
	s_barrier
	s_cbranch_vccz .LBB0_205
	s_barrier

; #define LDA(dst, b, h) for (int m = 0; m < 4; ++m) for (int k = 0; k < 2; ++k) \
;     dst[m][k] = *reinterpret_cast<const bf16x8*>((char*)SA(b, h) + lds_byte(wr * 64 + m * 16 + fr, k * 32 + fq * 8))
; #define LDB(dst, b, h) for (int n = 0; n < 2; ++n) for (int k = 0; k < 2; ++k) \
;     dst[n][k] = *reinterpret_cast<const bf16x8*>((char*)SB(b, h) + lds_byte(wc * 32 + n * 16 + fr, k * 32 + fq * 8))
; #define MMA(ai, bj, At, Bt_) do { __builtin_amdgcn_s_setprio(1); \
;     for (int m = 0; m < 4; ++m) for (int n = 0; n < 2; ++n) for (int k = 0; k < 2; ++k) \
;       acc[ai][bj][m][n] = __builtin_amdgcn_mfma_f32_16x16x32_bf16(At[m][k], Bt_[n][k], acc[ai][bj][m][n], 0, 0, 0); \
;     __builtin_amdgcn_s_setprio(0); } while (0)
; #define WAIT_L(n) asm volatile("s_waitcnt lgkmcnt(" #n ")" ::: "memory")
; #define BAR __builtin_amdgcn_s_barrier()
; #define SCHED __builtin_amdgcn_sched_barrier(0)
;     ...
;       LDB(B0, 0, 0); SCHED; LDA(At, 0, 0); STAGE(SA(1, 1), A, brow + HALF, t + 1);
;       WAIT_L(8); BAR; WAIT_L(0); MMA(0, 0, At, B0); BAR; SCHED;
;       LDB(B1, 0, 1); STAGE(SB(0, 0), Bt, bcol, t + 2);
;       BAR; WAIT_L(0); MMA(0, 1, At, B1); BAR;
;       LDA(At, 0, 1); STAGE(SA(0, 0), A, brow, t + 2);
;       BAR; WAIT_L(0); MMA(1, 0, At, B0); BAR; SCHED;
.LBB0_418:
	v_add_u32_e32 v143, s2, v142
	ds_read_b128 v[146:149], v143
	ds_read_b128 v[150:153], v143 offset:1024
	ds_read_b128 v[154:157], v143 offset:2048
	ds_read_b128 v[158:161], v143 offset:3072
	s_add_u32 s42, s30, s6
	s_addc_u32 s43, s31, s7
	s_add_u32 s44, s42, 0x80080
	s_addc_u32 s45, s43, 0
	s_add_i32 s41, s15, 0xc000
	ds_read_b128 v[162:165], v133
	ds_read_b128 v[184:187], v133 offset:1024
	ds_read_b128 v[188:191], v134
	ds_read_b128 v[192:195], v134 offset:1024
	ds_read_b128 v[196:199], v137
	ds_read_b128 v[200:203], v137 offset:1024
	ds_read_b128 v[204:207], v139
	ds_read_b128 v[208:211], v139 offset:1024
	s_mov_b32 m0, s41
	v_lshl_add_u64 v[144:145], s[44:45], 0, v[0:1]
	s_add_i32 s37, s15, 0xe000
	global_load_lds_dwordx4 v[144:145], off
	v_lshl_add_u64 v[144:145], s[44:45], 0, v[140:141]
	s_mov_b32 m0, s37
	s_nop 0
	global_load_lds_dwordx4 v[144:145], off
	s_waitcnt lgkmcnt(8)
	s_barrier
	s_waitcnt lgkmcnt(0)
	s_waitcnt lgkmcnt(0)
	v_mfma_f32_16x16x32_bf16 v[126:129], v[162:165], v[146:149], v[126:129]
	v_mfma_f32_16x16x32_bf16 v[122:125], v[162:165], v[154:157], v[122:125]
	v_mfma_f32_16x16x32_bf16 v[118:121], v[188:191], v[146:149], v[118:121]
	v_mfma_f32_16x16x32_bf16 v[114:117], v[188:191], v[154:157], v[114:117]
	v_mfma_f32_16x16x32_bf16 v[110:113], v[196:199], v[146:149], v[110:113]
	v_mfma_f32_16x16x32_bf16 v[106:109], v[196:199], v[154:157], v[106:109]
	v_mfma_f32_16x16x32_bf16 v[102:105], v[204:207], v[146:149], v[102:105]
	v_mfma_f32_16x16x32_bf16 v[98:101], v[204:207], v[154:157], v[98:101]
	v_mfma_f32_16x16x32_bf16 v[126:129], v[184:187], v[150:153], v[126:129]
	v_mfma_f32_16x16x32_bf16 v[122:125], v[184:187], v[158:161], v[122:125]
	v_mfma_f32_16x16x32_bf16 v[118:121], v[192:195], v[150:153], v[118:121]
	v_mfma_f32_16x16x32_bf16 v[114:117], v[192:195], v[158:161], v[114:117]
	v_mfma_f32_16x16x32_bf16 v[110:113], v[200:203], v[150:153], v[110:113]
	v_mfma_f32_16x16x32_bf16 v[106:109], v[200:203], v[158:161], v[106:109]
	v_mfma_f32_16x16x32_bf16 v[102:105], v[208:211], v[150:153], v[102:105]
	v_mfma_f32_16x16x32_bf16 v[98:101], v[208:211], v[158:161], v[98:101]
	s_barrier
	s_add_u32 s44, s34, s6
	s_addc_u32 s45, s35, s7
	s_add_u32 s50, s44, 0x100
	v_add_u32_e32 v144, s76, v142
	s_addc_u32 s51, s45, 0
	s_mov_b32 m0, s23
	ds_read_b128 v[212:215], v144
	ds_read_b128 v[216:219], v144 offset:1024
	ds_read_b128 v[220:223], v144 offset:2048
	ds_read_b128 v[224:227], v144 offset:3072
	s_nop 0
	v_lshl_add_u64 v[166:167], s[50:51], 0, v[0:1]
	global_load_lds_dwordx4 v[166:167], off
	v_lshl_add_u64 v[166:167], s[50:51], 0, v[140:141]
	s_mov_b32 m0, s26
	s_nop 0
	global_load_lds_dwordx4 v[166:167], off
	s_barrier
	s_waitcnt lgkmcnt(0)
	s_waitcnt lgkmcnt(0)
	v_mfma_f32_16x16x32_bf16 v[94:97], v[162:165], v[212:215], v[94:97]
	v_mfma_f32_16x16x32_bf16 v[90:93], v[162:165], v[220:223], v[90:93]
	v_mfma_f32_16x16x32_bf16 v[86:89], v[188:191], v[212:215], v[86:89]
	v_mfma_f32_16x16x32_bf16 v[82:85], v[188:191], v[220:223], v[82:85]
	v_mfma_f32_16x16x32_bf16 v[78:81], v[196:199], v[212:215], v[78:81]
	v_mfma_f32_16x16x32_bf16 v[74:77], v[196:199], v[220:223], v[74:77]
	v_mfma_f32_16x16x32_bf16 v[70:73], v[204:207], v[212:215], v[70:73]
	v_mfma_f32_16x16x32_bf16 v[66:69], v[204:207], v[220:223], v[66:69]
	v_mfma_f32_16x16x32_bf16 v[94:97], v[184:187], v[216:219], v[94:97]
	v_mfma_f32_16x16x32_bf16 v[90:93], v[184:187], v[224:227], v[90:93]
	v_mfma_f32_16x16x32_bf16 v[86:89], v[192:195], v[216:219], v[86:89]
	v_mfma_f32_16x16x32_bf16 v[82:85], v[192:195], v[224:227], v[82:85]
	v_mfma_f32_16x16x32_bf16 v[78:81], v[200:203], v[216:219], v[78:81]
	v_mfma_f32_16x16x32_bf16 v[74:77], v[200:203], v[224:227], v[74:77]
	v_mfma_f32_16x16x32_bf16 v[70:73], v[208:211], v[216:219], v[70:73]
	v_mfma_f32_16x16x32_bf16 v[66:69], v[208:211], v[224:227], v[66:69]
	s_barrier
	s_add_u32 s50, s42, 0x100
	s_addc_u32 s51, s43, 0
	s_mov_b32 m0, s15
	ds_read_b128 v[162:165], v133 offset:16384
	ds_read_b128 v[184:187], v133 offset:17408
	ds_read_b128 v[188:191], v134 offset:16384
	ds_read_b128 v[192:195], v134 offset:17408
	ds_read_b128 v[196:199], v137 offset:16384
	ds_read_b128 v[200:203], v137 offset:17408
	ds_read_b128 v[204:207], v139 offset:16384
	ds_read_b128 v[208:211], v139 offset:17408
	s_nop 0
	v_lshl_add_u64 v[166:167], s[50:51], 0, v[0:1]
	global_load_lds_dwordx4 v[166:167], off
	v_lshl_add_u64 v[166:167], s[50:51], 0, v[140:141]
	s_mov_b32 m0, s25
	s_nop 0
	global_load_lds_dwordx4 v[166:167], off
	s_barrier
	s_waitcnt lgkmcnt(0)
	s_waitcnt lgkmcnt(0)
	v_mfma_f32_16x16x32_bf16 v[62:65], v[162:165], v[146:149], v[62:65]
	v_mfma_f32_16x16x32_bf16 v[58:61], v[162:165], v[154:157], v[58:61]
	v_mfma_f32_16x16x32_bf16 v[54:57], v[188:191], v[146:149], v[54:57]
	v_mfma_f32_16x16x32_bf16 v[50:53], v[188:191], v[154:157], v[50:53]
	v_mfma_f32_16x16x32_bf16 v[46:49], v[196:199], v[146:149], v[46:49]
	v_mfma_f32_16x16x32_bf16 v[42:45], v[196:199], v[154:157], v[42:45]
	v_mfma_f32_16x16x32_bf16 v[38:41], v[204:207], v[146:149], v[38:41]
	v_mfma_f32_16x16x32_bf16 v[34:37], v[204:207], v[154:157], v[34:37]
	v_mfma_f32_16x16x32_bf16 v[62:65], v[184:187], v[150:153], v[62:65]
	v_mfma_f32_16x16x32_bf16 v[58:61], v[184:187], v[158:161], v[58:61]
	v_mfma_f32_16x16x32_bf16 v[54:57], v[192:195], v[150:153], v[54:57]
	v_mfma_f32_16x16x32_bf16 v[50:53], v[192:195], v[158:161], v[50:53]
	v_mfma_f32_16x16x32_bf16 v[46:49], v[200:203], v[150:153], v[46:49]
	v_mfma_f32_16x16x32_bf16 v[42:45], v[200:203], v[158:161], v[42:45]
	v_mfma_f32_16x16x32_bf16 v[38:41], v[208:211], v[150:153], v[38:41]
	v_mfma_f32_16x16x32_bf16 v[34:37], v[208:211], v[158:161], v[34:37]
	s_barrier
; #define LDA(dst, b, h) for (int m = 0; m < 4; ++m) for (int k = 0; k < 2; ++k) \
;     dst[m][k] = *reinterpret_cast<const bf16x8*>((char*)SA(b, h) + lds_byte(wr * 64 + m * 16 + fr, k * 32 + fq * 8))
; #define LDB(dst, b, h) for (int n = 0; n < 2; ++n) for (int k = 0; k < 2; ++k) \
;     dst[n][k] = *reinterpret_cast<const bf16x8*>((char*)SB(b, h) + lds_byte(wc * 32 + n * 16 + fr, k * 32 + fq * 8))
; #define MMA(ai, bj, At, Bt_) do { __builtin_amdgcn_s_setprio(1); \
;     for (int m = 0; m < 4; ++m) for (int n = 0; n < 2; ++n) for (int k = 0; k < 2; ++k) \
;       acc[ai][bj][m][n] = __builtin_amdgcn_mfma_f32_16x16x32_bf16(At[m][k], Bt_[n][k], acc[ai][bj][m][n], 0, 0, 0); \
;     __builtin_amdgcn_s_setprio(0); } while (0)
; #define WAIT_V(n) asm volatile("s_waitcnt vmcnt(" #n ")" ::: "memory")
; #define WAIT_L(n) asm volatile("s_waitcnt lgkmcnt(" #n ")" ::: "memory")
; #define BAR __builtin_amdgcn_s_barrier()
; #define SCHED __builtin_amdgcn_sched_barrier(0)
;     ...
;       STAGE(SB(0, 1), Bt, bcol + HALF, t + 2);
;       WAIT_V(6); BAR; MMA(1, 1, At, B1); BAR;
;       LDB(B0, 1, 0); SCHED; LDA(At, 1, 0); STAGE(SA(0, 1), A, brow + HALF, t + 2);
;       WAIT_L(8); BAR; WAIT_L(0); MMA(0, 0, At, B0); BAR; SCHED;
;       LDB(B1, 1, 1); STAGE(SB(1, 0), Bt, bcol, t + 3);
;       BAR; WAIT_L(0); MMA(0, 1, At, B1); BAR;
;       LDA(At, 1, 1); STAGE(SA(1, 0), A, brow, t + 3);
	s_add_u32 s50, s44, 0x80100
	s_addc_u32 s51, s45, 0
	s_mov_b32 m0, s27
	s_nop 0
	v_lshl_add_u64 v[146:147], s[50:51], 0, v[0:1]
	global_load_lds_dwordx4 v[146:147], off
	v_lshl_add_u64 v[146:147], s[50:51], 0, v[140:141]
	s_mov_b32 m0, s28
	s_nop 0
	global_load_lds_dwordx4 v[146:147], off
	s_waitcnt vmcnt(6)
	s_barrier
	v_mfma_f32_16x16x32_bf16 v[30:33], v[162:165], v[212:215], v[30:33]
	v_mfma_f32_16x16x32_bf16 v[26:29], v[162:165], v[220:223], v[26:29]
	v_mfma_f32_16x16x32_bf16 v[22:25], v[188:191], v[212:215], v[22:25]
	v_mfma_f32_16x16x32_bf16 v[18:21], v[188:191], v[220:223], v[18:21]
	v_mfma_f32_16x16x32_bf16 v[14:17], v[196:199], v[212:215], v[14:17]
	v_mfma_f32_16x16x32_bf16 v[10:13], v[196:199], v[220:223], v[10:13]
	v_mfma_f32_16x16x32_bf16 v[6:9], v[204:207], v[212:215], v[6:9]
	v_mfma_f32_16x16x32_bf16 v[2:5], v[204:207], v[220:223], v[2:5]
	v_mfma_f32_16x16x32_bf16 v[30:33], v[184:187], v[216:219], v[30:33]
	v_mfma_f32_16x16x32_bf16 v[26:29], v[184:187], v[224:227], v[26:29]
	v_mfma_f32_16x16x32_bf16 v[22:25], v[192:195], v[216:219], v[22:25]
	v_mfma_f32_16x16x32_bf16 v[18:21], v[192:195], v[224:227], v[18:21]
	v_mfma_f32_16x16x32_bf16 v[14:17], v[200:203], v[216:219], v[14:17]
	v_mfma_f32_16x16x32_bf16 v[10:13], v[200:203], v[224:227], v[10:13]
	v_mfma_f32_16x16x32_bf16 v[6:9], v[208:211], v[216:219], v[6:9]
	v_mfma_f32_16x16x32_bf16 v[2:5], v[208:211], v[224:227], v[2:5]
	s_barrier
	v_add_u32_e32 v145, s77, v142
	ds_read_b128 v[148:151], v145
	ds_read_b128 v[152:155], v145 offset:1024
	ds_read_b128 v[156:159], v145 offset:2048
	ds_read_b128 v[160:163], v145 offset:3072
	s_add_u32 s50, s42, 0x80100
	s_addc_u32 s51, s43, 0
	s_mov_b32 m0, s17
	ds_read_b128 v[164:167], v133 offset:32768
	ds_read_b128 v[184:187], v133 offset:33792
	ds_read_b128 v[188:191], v134 offset:32768
	ds_read_b128 v[192:195], v134 offset:33792
	ds_read_b128 v[196:199], v137 offset:32768
	ds_read_b128 v[200:203], v137 offset:33792
	ds_read_b128 v[204:207], v139 offset:32768
	ds_read_b128 v[208:211], v139 offset:33792
	s_nop 0
	v_lshl_add_u64 v[146:147], s[50:51], 0, v[0:1]
	global_load_lds_dwordx4 v[146:147], off
	v_lshl_add_u64 v[146:147], s[50:51], 0, v[140:141]
	s_mov_b32 m0, s29
	s_nop 0
	global_load_lds_dwordx4 v[146:147], off
	s_waitcnt lgkmcnt(8)
	s_barrier
	s_waitcnt lgkmcnt(0)
	s_waitcnt lgkmcnt(0)
	v_mfma_f32_16x16x32_bf16 v[126:129], v[164:167], v[148:151], v[126:129]
	v_mfma_f32_16x16x32_bf16 v[122:125], v[164:167], v[156:159], v[122:125]
	v_mfma_f32_16x16x32_bf16 v[118:121], v[188:191], v[148:151], v[118:121]
	v_mfma_f32_16x16x32_bf16 v[114:117], v[188:191], v[156:159], v[114:117]
	v_mfma_f32_16x16x32_bf16 v[110:113], v[196:199], v[148:151], v[110:113]
	v_mfma_f32_16x16x32_bf16 v[106:109], v[196:199], v[156:159], v[106:109]
	v_mfma_f32_16x16x32_bf16 v[102:105], v[204:207], v[148:151], v[102:105]
	v_mfma_f32_16x16x32_bf16 v[98:101], v[204:207], v[156:159], v[98:101]
	v_mfma_f32_16x16x32_bf16 v[126:129], v[184:187], v[152:155], v[126:129]
	v_mfma_f32_16x16x32_bf16 v[122:125], v[184:187], v[160:163], v[122:125]
	v_mfma_f32_16x16x32_bf16 v[118:121], v[192:195], v[152:155], v[118:121]
	v_mfma_f32_16x16x32_bf16 v[114:117], v[192:195], v[160:163], v[114:117]
	v_mfma_f32_16x16x32_bf16 v[110:113], v[200:203], v[152:155], v[110:113]
	v_mfma_f32_16x16x32_bf16 v[106:109], v[200:203], v[160:163], v[106:109]
	v_mfma_f32_16x16x32_bf16 v[102:105], v[208:211], v[152:155], v[102:105]
	v_mfma_f32_16x16x32_bf16 v[98:101], v[208:211], v[160:163], v[98:101]
	s_barrier
	s_add_u32 s50, s44, 0x180
	v_add_u32_e32 v146, s78, v142
	s_addc_u32 s51, s45, 0
	s_mov_b32 m0, s8
	ds_read_b128 v[212:215], v146
	ds_read_b128 v[216:219], v146 offset:1024
	ds_read_b128 v[220:223], v146 offset:2048
	ds_read_b128 v[224:227], v146 offset:3072
	s_nop 0
	v_lshl_add_u64 v[228:229], s[50:51], 0, v[0:1]
	global_load_lds_dwordx4 v[228:229], off
	v_lshl_add_u64 v[228:229], s[50:51], 0, v[140:141]
	s_mov_b32 m0, s9
	s_nop 0
	global_load_lds_dwordx4 v[228:229], off
	s_barrier
	s_waitcnt lgkmcnt(0)
	s_waitcnt lgkmcnt(0)
	v_mfma_f32_16x16x32_bf16 v[94:97], v[164:167], v[212:215], v[94:97]
	v_mfma_f32_16x16x32_bf16 v[90:93], v[164:167], v[220:223], v[90:93]
	v_mfma_f32_16x16x32_bf16 v[86:89], v[188:191], v[212:215], v[86:89]
	v_mfma_f32_16x16x32_bf16 v[82:85], v[188:191], v[220:223], v[82:85]
	v_mfma_f32_16x16x32_bf16 v[78:81], v[196:199], v[212:215], v[78:81]
	v_mfma_f32_16x16x32_bf16 v[74:77], v[196:199], v[220:223], v[74:77]
	v_mfma_f32_16x16x32_bf16 v[70:73], v[204:207], v[212:215], v[70:73]
	v_mfma_f32_16x16x32_bf16 v[66:69], v[204:207], v[220:223], v[66:69]
	v_mfma_f32_16x16x32_bf16 v[94:97], v[184:187], v[216:219], v[94:97]
	v_mfma_f32_16x16x32_bf16 v[90:93], v[184:187], v[224:227], v[90:93]
	v_mfma_f32_16x16x32_bf16 v[86:89], v[192:195], v[216:219], v[86:89]
	v_mfma_f32_16x16x32_bf16 v[82:85], v[192:195], v[224:227], v[82:85]
	v_mfma_f32_16x16x32_bf16 v[78:81], v[200:203], v[216:219], v[78:81]
	v_mfma_f32_16x16x32_bf16 v[74:77], v[200:203], v[224:227], v[74:77]
	v_mfma_f32_16x16x32_bf16 v[70:73], v[208:211], v[216:219], v[70:73]
	v_mfma_f32_16x16x32_bf16 v[66:69], v[208:211], v[224:227], v[66:69]
	s_barrier
	s_add_u32 s42, s42, 0x180
	s_addc_u32 s43, s43, 0
	s_mov_b32 m0, s18
	ds_read_b128 v[164:167], v133 offset:49152
	ds_read_b128 v[184:187], v133 offset:50176
	ds_read_b128 v[188:191], v134 offset:49152
	ds_read_b128 v[192:195], v134 offset:50176
	ds_read_b128 v[196:199], v137 offset:49152
	ds_read_b128 v[200:203], v137 offset:50176
	ds_read_b128 v[204:207], v139 offset:49152
	ds_read_b128 v[208:211], v139 offset:50176
	s_nop 0
	v_lshl_add_u64 v[228:229], s[42:43], 0, v[0:1]
	global_load_lds_dwordx4 v[228:229], off
	v_lshl_add_u64 v[228:229], s[42:43], 0, v[140:141]
	s_mov_b32 m0, s19
	s_nop 0
	global_load_lds_dwordx4 v[228:229], off
	s_barrier
; #define LDA(dst, b, h) for (int m = 0; m < 4; ++m) for (int k = 0; k < 2; ++k) \
;     dst[m][k] = *reinterpret_cast<const bf16x8*>((char*)SA(b, h) + lds_byte(wr * 64 + m * 16 + fr, k * 32 + fq * 8))
; #define LDB(dst, b, h) for (int n = 0; n < 2; ++n) for (int k = 0; k < 2; ++k) \
;     dst[n][k] = *reinterpret_cast<const bf16x8*>((char*)SB(b, h) + lds_byte(wc * 32 + n * 16 + fr, k * 32 + fq * 8))
; #define MMA(ai, bj, At, Bt_) do { __builtin_amdgcn_s_setprio(1); \
;     for (int m = 0; m < 4; ++m) for (int n = 0; n < 2; ++n) for (int k = 0; k < 2; ++k) \
;       acc[ai][bj][m][n] = __builtin_amdgcn_mfma_f32_16x16x32_bf16(At[m][k], Bt_[n][k], acc[ai][bj][m][n], 0, 0, 0); \
;     __builtin_amdgcn_s_setprio(0); } while (0)
; #define WAIT_V(n) asm volatile("s_waitcnt vmcnt(" #n ")" ::: "memory")
; #define WAIT_L(n) asm volatile("s_waitcnt lgkmcnt(" #n ")" ::: "memory")
; #define BAR __builtin_amdgcn_s_barrier()
; #define SCHED __builtin_amdgcn_sched_barrier(0)
;     ...
;       BAR; WAIT_L(0); MMA(1, 0, At, B0); BAR; SCHED;
;       STAGE(SB(1, 1), Bt, bcol + HALF, t + 3);
;       WAIT_V(6); BAR; MMA(1, 1, At, B1); BAR;
;     }
;     { LDB(B0, 0, 0); LDA(At, 0, 0); STAGE(SA(1, 1), A, brow + HALF, nt - 1);
;       BAR; WAIT_L(0); MMA(0, 0, At, B0); BAR;
;       LDB(B1, 0, 1); BAR; WAIT_L(0); MMA(0, 1, At, B1); BAR;
	s_waitcnt lgkmcnt(0)
	s_waitcnt lgkmcnt(0)
	v_mfma_f32_16x16x32_bf16 v[62:65], v[164:167], v[148:151], v[62:65]
	v_mfma_f32_16x16x32_bf16 v[58:61], v[164:167], v[156:159], v[58:61]
	v_mfma_f32_16x16x32_bf16 v[54:57], v[188:191], v[148:151], v[54:57]
	v_mfma_f32_16x16x32_bf16 v[50:53], v[188:191], v[156:159], v[50:53]
	v_mfma_f32_16x16x32_bf16 v[46:49], v[196:199], v[148:151], v[46:49]
	v_mfma_f32_16x16x32_bf16 v[42:45], v[196:199], v[156:159], v[42:45]
	v_mfma_f32_16x16x32_bf16 v[38:41], v[204:207], v[148:151], v[38:41]
	v_mfma_f32_16x16x32_bf16 v[34:37], v[204:207], v[156:159], v[34:37]
	v_mfma_f32_16x16x32_bf16 v[62:65], v[184:187], v[152:155], v[62:65]
	v_mfma_f32_16x16x32_bf16 v[58:61], v[184:187], v[160:163], v[58:61]
	v_mfma_f32_16x16x32_bf16 v[54:57], v[192:195], v[152:155], v[54:57]
	v_mfma_f32_16x16x32_bf16 v[50:53], v[192:195], v[160:163], v[50:53]
	v_mfma_f32_16x16x32_bf16 v[46:49], v[200:203], v[152:155], v[46:49]
	v_mfma_f32_16x16x32_bf16 v[42:45], v[200:203], v[160:163], v[42:45]
	v_mfma_f32_16x16x32_bf16 v[38:41], v[208:211], v[152:155], v[38:41]
	v_mfma_f32_16x16x32_bf16 v[34:37], v[208:211], v[160:163], v[34:37]
	s_barrier
	s_add_u32 s42, s44, 0x80180
	s_addc_u32 s43, s45, 0
	s_mov_b32 m0, s20
	s_nop 0
	v_lshl_add_u64 v[148:149], s[42:43], 0, v[0:1]
	global_load_lds_dwordx4 v[148:149], off
	v_lshl_add_u64 v[148:149], s[42:43], 0, v[140:141]
	s_mov_b32 m0, s21
	s_nop 0
	global_load_lds_dwordx4 v[148:149], off
	s_add_i32 s36, s36, 2
	s_add_u32 s6, s6, 0x100
	s_addc_u32 s7, s7, 0
	s_cmp_gt_u32 s36, 27
	s_waitcnt vmcnt(6)
	s_barrier
	v_mfma_f32_16x16x32_bf16 v[30:33], v[164:167], v[212:215], v[30:33]
	v_mfma_f32_16x16x32_bf16 v[26:29], v[164:167], v[220:223], v[26:29]
	v_mfma_f32_16x16x32_bf16 v[22:25], v[188:191], v[212:215], v[22:25]
	v_mfma_f32_16x16x32_bf16 v[18:21], v[188:191], v[220:223], v[18:21]
	v_mfma_f32_16x16x32_bf16 v[14:17], v[196:199], v[212:215], v[14:17]
	v_mfma_f32_16x16x32_bf16 v[10:13], v[196:199], v[220:223], v[10:13]
	v_mfma_f32_16x16x32_bf16 v[6:9], v[204:207], v[212:215], v[6:9]
	v_mfma_f32_16x16x32_bf16 v[2:5], v[204:207], v[220:223], v[2:5]
	v_mfma_f32_16x16x32_bf16 v[30:33], v[184:187], v[216:219], v[30:33]
	v_mfma_f32_16x16x32_bf16 v[26:29], v[184:187], v[224:227], v[26:29]
	v_mfma_f32_16x16x32_bf16 v[22:25], v[192:195], v[216:219], v[22:25]
	v_mfma_f32_16x16x32_bf16 v[18:21], v[192:195], v[224:227], v[18:21]
	v_mfma_f32_16x16x32_bf16 v[14:17], v[200:203], v[216:219], v[14:17]
	v_mfma_f32_16x16x32_bf16 v[10:13], v[200:203], v[224:227], v[10:13]
	v_mfma_f32_16x16x32_bf16 v[6:9], v[208:211], v[216:219], v[6:9]
	v_mfma_f32_16x16x32_bf16 v[2:5], v[208:211], v[224:227], v[2:5]
	s_barrier
	s_cbranch_scc0 .LBB0_418
	s_add_u32 s4, s4, 0xf80
	s_addc_u32 s5, s5, 0
	s_mov_b32 m0, s41
	ds_read_b128 v[148:151], v143
	ds_read_b128 v[152:155], v143 offset:1024
	ds_read_b128 v[156:159], v143 offset:2048
	ds_read_b128 v[160:163], v143 offset:3072
	ds_read_b128 v[164:167], v133
	ds_read_b128 v[184:187], v133 offset:1024
	ds_read_b128 v[188:191], v134
	ds_read_b128 v[192:195], v134 offset:1024
	ds_read_b128 v[196:199], v137
	ds_read_b128 v[200:203], v137 offset:1024
	ds_read_b128 v[204:207], v139
	ds_read_b128 v[208:211], v139 offset:1024
	s_nop 0
	v_lshl_add_u64 v[142:143], s[4:5], 0, v[0:1]
	global_load_lds_dwordx4 v[142:143], off
	v_lshl_add_u64 v[140:141], s[4:5], 0, v[140:141]
	s_mov_b32 m0, s37
	s_nop 0
	global_load_lds_dwordx4 v[140:141], off
	s_barrier
	s_waitcnt lgkmcnt(0)
	s_waitcnt lgkmcnt(0)
	v_mfma_f32_16x16x32_bf16 v[126:129], v[164:167], v[148:151], v[126:129]
	v_mfma_f32_16x16x32_bf16 v[122:125], v[164:167], v[156:159], v[122:125]
	v_mfma_f32_16x16x32_bf16 v[118:121], v[188:191], v[148:151], v[118:121]
	v_mfma_f32_16x16x32_bf16 v[110:113], v[196:199], v[148:151], v[110:113]
	v_mfma_f32_16x16x32_bf16 v[106:109], v[196:199], v[156:159], v[106:109]
	v_mfma_f32_16x16x32_bf16 v[102:105], v[204:207], v[148:151], v[102:105]
	v_mfma_f32_16x16x32_bf16 v[98:101], v[204:207], v[156:159], v[98:101]
	v_mfma_f32_16x16x32_bf16 v[126:129], v[184:187], v[152:155], v[126:129]
	v_mfma_f32_16x16x32_bf16 v[122:125], v[184:187], v[160:163], v[122:125]
	v_mfma_f32_16x16x32_bf16 v[118:121], v[192:195], v[152:155], v[118:121]
	v_mfma_f32_16x16x32_bf16 v[114:117], v[188:191], v[156:159], v[114:117]
	v_mfma_f32_16x16x32_bf16 v[110:113], v[200:203], v[152:155], v[110:113]
	v_mfma_f32_16x16x32_bf16 v[106:109], v[200:203], v[160:163], v[106:109]
	v_mfma_f32_16x16x32_bf16 v[102:105], v[208:211], v[152:155], v[102:105]
	v_mfma_f32_16x16x32_bf16 v[98:101], v[208:211], v[160:163], v[98:101]
	v_mfma_f32_16x16x32_bf16 v[140:143], v[192:195], v[160:163], v[114:117]
	s_barrier
	s_nop 0
	ds_read_b128 v[114:117], v144
	ds_read_b128 v[212:215], v144 offset:1024
	ds_read_b128 v[216:219], v144 offset:2048
	ds_read_b128 v[220:223], v144 offset:3072
	s_barrier
	s_waitcnt lgkmcnt(0)
	s_waitcnt lgkmcnt(0)
	v_mfma_f32_16x16x32_bf16 v[90:93], v[164:167], v[216:219], v[90:93]
	v_mfma_f32_16x16x32_bf16 v[86:89], v[188:191], v[114:117], v[86:89]
	v_mfma_f32_16x16x32_bf16 v[94:97], v[164:167], v[114:117], v[94:97]
	v_mfma_f32_16x16x32_bf16 v[90:93], v[184:187], v[220:223], v[90:93]
	v_mfma_f32_16x16x32_bf16 v[86:89], v[192:195], v[212:215], v[86:89]
	v_mfma_f32_16x16x32_bf16 v[82:85], v[188:191], v[216:219], v[82:85]
	v_mfma_f32_16x16x32_bf16 v[78:81], v[196:199], v[114:117], v[78:81]
	v_mfma_f32_16x16x32_bf16 v[74:77], v[196:199], v[216:219], v[74:77]
	v_mfma_f32_16x16x32_bf16 v[70:73], v[204:207], v[114:117], v[70:73]
	v_mfma_f32_16x16x32_bf16 v[66:69], v[204:207], v[216:219], v[66:69]
	v_mfma_f32_16x16x32_bf16 v[224:227], v[184:187], v[212:215], v[94:97]
	v_mfma_f32_16x16x32_bf16 v[164:167], v[192:195], v[220:223], v[82:85]
	v_mfma_f32_16x16x32_bf16 v[184:187], v[200:203], v[212:215], v[78:81]
	v_mfma_f32_16x16x32_bf16 v[188:191], v[200:203], v[220:223], v[74:77]
	v_mfma_f32_16x16x32_bf16 v[192:195], v[208:211], v[212:215], v[70:73]
	v_mfma_f32_16x16x32_bf16 v[196:199], v[208:211], v[220:223], v[66:69]
	s_barrier
; #define LDA(dst, b, h) for (int m = 0; m < 4; ++m) for (int k = 0; k < 2; ++k) \
;     dst[m][k] = *reinterpret_cast<const bf16x8*>((char*)SA(b, h) + lds_byte(wr * 64 + m * 16 + fr, k * 32 + fq * 8))
; #define LDB(dst, b, h) for (int n = 0; n < 2; ++n) for (int k = 0; k < 2; ++k) \
;     dst[n][k] = *reinterpret_cast<const bf16x8*>((char*)SB(b, h) + lds_byte(wc * 32 + n * 16 + fr, k * 32 + fq * 8))
; #define MMA(ai, bj, At, Bt_) do { __builtin_amdgcn_s_setprio(1); \
;     for (int m = 0; m < 4; ++m) for (int n = 0; n < 2; ++n) for (int k = 0; k < 2; ++k) \
;       acc[ai][bj][m][n] = __builtin_amdgcn_mfma_f32_16x16x32_bf16(At[m][k], Bt_[n][k], acc[ai][bj][m][n], 0, 0, 0); \
;     __builtin_amdgcn_s_setprio(0); } while (0)
; #define WAIT_V(n) asm volatile("s_waitcnt vmcnt(" #n ")" ::: "memory")
; #define WAIT_L(n) asm volatile("s_waitcnt lgkmcnt(" #n ")" ::: "memory")
; #define BAR __builtin_amdgcn_s_barrier()
;     ...
;       LDA(At, 0, 1); WAIT_V(4); BAR; WAIT_L(0); MMA(1, 0, At, B0); MMA(1, 1, At, B1); BAR; }
;     { LDB(B0, 1, 0); LDA(At, 1, 0); WAIT_V(2); BAR; WAIT_L(0); MMA(0, 0, At, B0); BAR;
	s_nop 0
	ds_read_b128 v[66:69], v133 offset:16384
	ds_read_b128 v[70:73], v133 offset:17408
	ds_read_b128 v[74:77], v134 offset:16384
	ds_read_b128 v[78:81], v134 offset:17408
	ds_read_b128 v[82:85], v137 offset:16384
	ds_read_b128 v[94:97], v137 offset:17408
	ds_read_b128 v[200:203], v139 offset:16384
	ds_read_b128 v[204:207], v139 offset:17408
	s_waitcnt vmcnt(4)
	s_barrier
	s_waitcnt lgkmcnt(0)
	s_waitcnt lgkmcnt(0)
	v_mfma_f32_16x16x32_bf16 v[62:65], v[66:69], v[148:151], v[62:65]
	v_mfma_f32_16x16x32_bf16 v[58:61], v[66:69], v[156:159], v[58:61]
	v_mfma_f32_16x16x32_bf16 v[54:57], v[74:77], v[148:151], v[54:57]
	v_mfma_f32_16x16x32_bf16 v[50:53], v[74:77], v[156:159], v[50:53]
	v_mfma_f32_16x16x32_bf16 v[46:49], v[82:85], v[148:151], v[46:49]
	v_mfma_f32_16x16x32_bf16 v[42:45], v[82:85], v[156:159], v[42:45]
	v_mfma_f32_16x16x32_bf16 v[38:41], v[200:203], v[148:151], v[38:41]
	v_mfma_f32_16x16x32_bf16 v[34:37], v[200:203], v[156:159], v[34:37]
	v_mfma_f32_16x16x32_bf16 v[62:65], v[70:73], v[152:155], v[62:65]
	v_mfma_f32_16x16x32_bf16 v[58:61], v[70:73], v[160:163], v[58:61]
	v_mfma_f32_16x16x32_bf16 v[54:57], v[78:81], v[152:155], v[54:57]
	v_mfma_f32_16x16x32_bf16 v[50:53], v[78:81], v[160:163], v[50:53]
	v_mfma_f32_16x16x32_bf16 v[46:49], v[94:97], v[152:155], v[46:49]
	v_mfma_f32_16x16x32_bf16 v[42:45], v[94:97], v[160:163], v[42:45]
	v_mfma_f32_16x16x32_bf16 v[38:41], v[204:207], v[152:155], v[38:41]
	v_mfma_f32_16x16x32_bf16 v[34:37], v[204:207], v[160:163], v[34:37]
	v_mfma_f32_16x16x32_bf16 v[30:33], v[66:69], v[114:117], v[30:33]
	v_mfma_f32_16x16x32_bf16 v[26:29], v[66:69], v[216:219], v[26:29]
	v_mfma_f32_16x16x32_bf16 v[22:25], v[74:77], v[114:117], v[22:25]
	v_mfma_f32_16x16x32_bf16 v[18:21], v[74:77], v[216:219], v[18:21]
	v_mfma_f32_16x16x32_bf16 v[14:17], v[82:85], v[114:117], v[14:17]
	v_mfma_f32_16x16x32_bf16 v[10:13], v[82:85], v[216:219], v[10:13]
	v_mfma_f32_16x16x32_bf16 v[6:9], v[200:203], v[114:117], v[6:9]
	v_mfma_f32_16x16x32_bf16 v[2:5], v[200:203], v[216:219], v[2:5]
	v_mfma_f32_16x16x32_bf16 v[148:151], v[70:73], v[212:215], v[30:33]
	v_mfma_f32_16x16x32_bf16 v[152:155], v[70:73], v[220:223], v[26:29]
	v_mfma_f32_16x16x32_bf16 v[156:159], v[78:81], v[212:215], v[22:25]
	v_mfma_f32_16x16x32_bf16 v[160:163], v[78:81], v[220:223], v[18:21]
	v_mfma_f32_16x16x32_bf16 v[208:211], v[94:97], v[212:215], v[14:17]
	v_mfma_f32_16x16x32_bf16 v[228:231], v[94:97], v[220:223], v[10:13]
	v_mfma_f32_16x16x32_bf16 v[212:215], v[204:207], v[212:215], v[6:9]
	v_mfma_f32_16x16x32_bf16 v[200:203], v[204:207], v[220:223], v[2:5]
	s_barrier
	ds_read_b128 v[14:17], v145
	ds_read_b128 v[30:33], v145 offset:1024
	ds_read_b128 v[204:207], v145 offset:2048
	ds_read_b128 v[216:219], v145 offset:3072
	ds_read_b128 v[2:5], v133 offset:32768
	ds_read_b128 v[6:9], v133 offset:33792
	ds_read_b128 v[10:13], v134 offset:32768
	ds_read_b128 v[18:21], v134 offset:33792
	ds_read_b128 v[22:25], v137 offset:32768
	ds_read_b128 v[26:29], v137 offset:33792
	ds_read_b128 v[220:223], v139 offset:32768
	ds_read_b128 v[232:235], v139 offset:33792
	s_waitcnt vmcnt(2)
	s_barrier
	s_waitcnt lgkmcnt(0)
	s_waitcnt lgkmcnt(0)
	v_mfma_f32_16x16x32_bf16 v[66:69], v[2:5], v[14:17], v[126:129]
	v_mfma_f32_16x16x32_bf16 v[114:117], v[6:9], v[30:33], v[66:69]
	v_mfma_f32_16x16x32_bf16 v[66:69], v[2:5], v[204:207], v[122:125]
	v_mfma_f32_16x16x32_bf16 v[126:129], v[6:9], v[216:219], v[66:69]
	v_mfma_f32_16x16x32_bf16 v[66:69], v[10:13], v[14:17], v[118:121]
	v_mfma_f32_16x16x32_bf16 v[82:85], v[18:21], v[30:33], v[66:69]
	v_mfma_f32_16x16x32_bf16 v[66:69], v[10:13], v[204:207], v[140:143]
	v_mfma_f32_16x16x32_bf16 v[94:97], v[18:21], v[216:219], v[66:69]
	v_mfma_f32_16x16x32_bf16 v[66:69], v[22:25], v[14:17], v[110:113]
	v_mfma_f32_16x16x32_bf16 v[74:77], v[26:29], v[30:33], v[66:69]
	v_mfma_f32_16x16x32_bf16 v[66:69], v[22:25], v[204:207], v[106:109]
	v_mfma_f32_16x16x32_bf16 v[78:81], v[26:29], v[216:219], v[66:69]
	v_mfma_f32_16x16x32_bf16 v[66:69], v[220:223], v[14:17], v[102:105]
	v_mfma_f32_16x16x32_bf16 v[70:73], v[220:223], v[204:207], v[98:101]
	v_mfma_f32_16x16x32_bf16 v[66:69], v[232:235], v[30:33], v[66:69]
	v_mfma_f32_16x16x32_bf16 v[70:73], v[232:235], v[216:219], v[70:73]
	s_barrier
; #define LDA(dst, b, h) for (int m = 0; m < 4; ++m) for (int k = 0; k < 2; ++k) \
;     dst[m][k] = *reinterpret_cast<const bf16x8*>((char*)SA(b, h) + lds_byte(wr * 64 + m * 16 + fr, k * 32 + fq * 8))
; #define LDB(dst, b, h) for (int n = 0; n < 2; ++n) for (int k = 0; k < 2; ++k) \
;     dst[n][k] = *reinterpret_cast<const bf16x8*>((char*)SB(b, h) + lds_byte(wc * 32 + n * 16 + fr, k * 32 + fq * 8))
; #define MMA(ai, bj, At, Bt_) do { __builtin_amdgcn_s_setprio(1); \
;     for (int m = 0; m < 4; ++m) for (int n = 0; n < 2; ++n) for (int k = 0; k < 2; ++k) \
;       acc[ai][bj][m][n] = __builtin_amdgcn_mfma_f32_16x16x32_bf16(At[m][k], Bt_[n][k], acc[ai][bj][m][n], 0, 0, 0); \
;     __builtin_amdgcn_s_setprio(0); } while (0)
; #define WAIT_V(n) asm volatile("s_waitcnt vmcnt(" #n ")" ::: "memory")
; #define WAIT_L(n) asm volatile("s_waitcnt lgkmcnt(" #n ")" ::: "memory")
; #define BAR __builtin_amdgcn_s_barrier()
;     ...
;     { LDB(B0, 1, 0); LDA(At, 1, 0); WAIT_V(2); BAR; WAIT_L(0); MMA(0, 0, At, B0); BAR;
;       LDB(B1, 1, 1); WAIT_V(0); BAR; WAIT_L(0); MMA(0, 1, At, B1); BAR;
;       LDA(At, 1, 1); BAR; WAIT_L(0); MMA(1, 0, At, B0); MMA(1, 1, At, B1); BAR; }
;     if (wr == 0) BAR;
	ds_read_b128 v[140:143], v146
	ds_read_b128 v[236:239], v146 offset:1024
	ds_read_b128 v[240:243], v146 offset:2048
	ds_read_b128 v[144:147], v146 offset:3072
	s_waitcnt vmcnt(0)
	s_barrier
	s_waitcnt lgkmcnt(0)
	s_waitcnt lgkmcnt(0)
	v_mfma_f32_16x16x32_bf16 v[98:101], v[2:5], v[140:143], v[224:227]
	v_mfma_f32_16x16x32_bf16 v[2:5], v[2:5], v[240:243], v[90:93]
	v_mfma_f32_16x16x32_bf16 v[118:121], v[6:9], v[144:147], v[2:5]
	v_mfma_f32_16x16x32_bf16 v[2:5], v[10:13], v[140:143], v[86:89]
	v_mfma_f32_16x16x32_bf16 v[102:105], v[18:21], v[236:239], v[2:5]
	v_mfma_f32_16x16x32_bf16 v[2:5], v[10:13], v[240:243], v[164:167]
	v_mfma_f32_16x16x32_bf16 v[122:125], v[18:21], v[144:147], v[2:5]
	v_mfma_f32_16x16x32_bf16 v[2:5], v[22:25], v[140:143], v[184:187]
	v_mfma_f32_16x16x32_bf16 v[90:93], v[26:29], v[236:239], v[2:5]
	v_mfma_f32_16x16x32_bf16 v[2:5], v[22:25], v[240:243], v[188:191]
	v_mfma_f32_16x16x32_bf16 v[110:113], v[26:29], v[144:147], v[2:5]
	v_mfma_f32_16x16x32_bf16 v[2:5], v[220:223], v[140:143], v[192:195]
	v_mfma_f32_16x16x32_bf16 v[86:89], v[232:235], v[236:239], v[2:5]
	v_mfma_f32_16x16x32_bf16 v[2:5], v[220:223], v[240:243], v[196:199]
	v_mfma_f32_16x16x32_bf16 v[98:101], v[6:9], v[236:239], v[98:101]
	v_mfma_f32_16x16x32_bf16 v[106:109], v[232:235], v[144:147], v[2:5]
	s_barrier
	ds_read_b128 v[164:167], v133 offset:49152
	ds_read_b128 v[184:187], v133 offset:50176
	ds_read_b128 v[188:191], v134 offset:49152
	ds_read_b128 v[192:195], v134 offset:50176
	ds_read_b128 v[196:199], v137 offset:49152
	ds_read_b128 v[220:223], v137 offset:50176
	ds_read_b128 v[224:227], v139 offset:49152
	ds_read_b128 v[232:235], v139 offset:50176
	s_barrier
	s_waitcnt lgkmcnt(0)
	s_waitcnt lgkmcnt(0)
	v_mfma_f32_16x16x32_bf16 v[6:9], v[164:167], v[204:207], v[58:61]
	v_mfma_f32_16x16x32_bf16 v[10:13], v[188:191], v[204:207], v[50:53]
	v_mfma_f32_16x16x32_bf16 v[2:5], v[164:167], v[14:17], v[62:65]
	v_mfma_f32_16x16x32_bf16 v[18:21], v[184:187], v[216:219], v[6:9]
	v_mfma_f32_16x16x32_bf16 v[6:9], v[188:191], v[14:17], v[54:57]
	v_mfma_f32_16x16x32_bf16 v[22:25], v[192:195], v[216:219], v[10:13]
	v_mfma_f32_16x16x32_bf16 v[10:13], v[196:199], v[14:17], v[46:49]
	v_mfma_f32_16x16x32_bf16 v[14:17], v[224:227], v[14:17], v[38:41]
	v_mfma_f32_16x16x32_bf16 v[2:5], v[184:187], v[30:33], v[2:5]
	v_mfma_f32_16x16x32_bf16 v[6:9], v[192:195], v[30:33], v[6:9]
	v_mfma_f32_16x16x32_bf16 v[10:13], v[220:223], v[30:33], v[10:13]
	v_mfma_f32_16x16x32_bf16 v[26:29], v[196:199], v[204:207], v[42:45]
	v_mfma_f32_16x16x32_bf16 v[14:17], v[232:235], v[30:33], v[14:17]
	v_mfma_f32_16x16x32_bf16 v[30:33], v[224:227], v[204:207], v[34:37]
	v_mfma_f32_16x16x32_bf16 v[26:29], v[220:223], v[216:219], v[26:29]
	v_mfma_f32_16x16x32_bf16 v[30:33], v[232:235], v[216:219], v[30:33]
	v_mfma_f32_16x16x32_bf16 v[38:41], v[164:167], v[240:243], v[152:155]
	v_mfma_f32_16x16x32_bf16 v[42:45], v[188:191], v[240:243], v[160:163]
	v_mfma_f32_16x16x32_bf16 v[46:49], v[196:199], v[240:243], v[228:231]
	v_mfma_f32_16x16x32_bf16 v[34:37], v[164:167], v[140:143], v[148:151]
	v_mfma_f32_16x16x32_bf16 v[50:53], v[184:187], v[144:147], v[38:41]
	v_mfma_f32_16x16x32_bf16 v[38:41], v[188:191], v[140:143], v[156:159]
	v_mfma_f32_16x16x32_bf16 v[54:57], v[192:195], v[144:147], v[42:45]
	v_mfma_f32_16x16x32_bf16 v[42:45], v[196:199], v[140:143], v[208:211]
	v_mfma_f32_16x16x32_bf16 v[58:61], v[220:223], v[144:147], v[46:49]
	v_mfma_f32_16x16x32_bf16 v[46:49], v[224:227], v[140:143], v[212:215]
	v_mfma_f32_16x16x32_bf16 v[62:65], v[224:227], v[240:243], v[200:203]
	v_mfma_f32_16x16x32_bf16 v[34:37], v[184:187], v[236:239], v[34:37]
	v_mfma_f32_16x16x32_bf16 v[38:41], v[192:195], v[236:239], v[38:41]
	v_mfma_f32_16x16x32_bf16 v[42:45], v[220:223], v[236:239], v[42:45]
	v_mfma_f32_16x16x32_bf16 v[46:49], v[232:235], v[236:239], v[46:49]
	v_mfma_f32_16x16x32_bf16 v[62:65], v[232:235], v[144:147], v[62:65]
	v_readlane_b32 s4, v245, 33
	v_readlane_b32 s5, v245, 34
	s_and_b64 vcc, exec, s[4:5]
	s_barrier
	s_cbranch_vccz .LBB0_421
	s_barrier
